# GEMM epilogues (bf16 Y partials and SwiGLU act): lane-pair exchange via v_permlane16_swap so each lane stores 16 B (dwordx4) instead of two 8 B stores
# speedup vs baseline: 1.0136x; 1.0136x over previous
; #define PG8_STAGE(bufoff, gbase, voff) do { _Pragma("unroll") for (int _i = 0; _i < 2; ++_i) \
;         __builtin_amdgcn_global_load_lds((const unsigned*)((const char*)(gbase) + (voff)[_i]), (LAS unsigned*)(lds + (bufoff) + ldsw + _i * 8192), 16, 0, 0); } while (0)
; #define PG8_LDA(dst, b, h) do { _Pragma("unroll") for (int m = 0; m < 4; ++m) _Pragma("unroll") for (int k = 0; k < 2; ++k) dst[m][k] = *(const LAS bf16x8*)(lds + PG8_SA(b, h) + aoff + m * 2048 + k * 1024); } while (0)
; #define PG8_LDB(dst, b, h) do { _Pragma("unroll") for (int n = 0; n < 2; ++n) _Pragma("unroll") for (int k = 0; k < 2; ++k) dst[n][k] = *(const LAS bf16x8*)(lds + PG8_SB(b, h) + boff + n * 2048 + k * 1024); } while (0)
; #define PG8_BAR __builtin_amdgcn_s_barrier()
; template <class Epi>
; __device__ __forceinline__ void gemm_phase(const int tid, LAS unsigned char* lds, const Gemm g, const StaticOrder& S, const Epi& E) {
;     ...
;     for (int t = 0; t < nt; t += 2) {
;       const bool last = (t == nt - 2);
;       const char* a1 = cA + (size_t)(t + 1) * kstep;
;       const char* a2 = last ? nA : cA + (size_t)(t + 2) * kstep; const char* b2 = last ? nB : cB + (size_t)(t + 2) * kstep;
;       const char* a3 = a2 + kstep; const char* b3 = b2 + kstep;
;       PG8_LDB(B0, 0, 0); PG8_SCHED; PG8_LDA(At, 0, 0); PG8_STAGE(PG8_SA(1, 1), a1 + hstep, voffA);
;       PG8_WAIT_L(8); PG8_BAR; PG8_WAIT_L(0); PG8_MMA(0, 0, At, B0); PG8_BAR; PG8_SCHED;
;       PG8_LDB(B1, 0, 1); PG8_STAGE(PG8_SB(0, 0), b2, voffA);
;       PG8_BAR; PG8_WAIT_L(0); PG8_MMA(0, 1, At, B1); PG8_BAR;
;       PG8_LDA(At, 0, 1); PG8_STAGE(PG8_SA(0, 0), a2, voffA);
;       PG8_BAR; PG8_WAIT_L(0); PG8_MMA(1, 0, At, B0); PG8_BAR; PG8_SCHED;
;       PG8_STAGE(PG8_SB(0, 1), b2 + hstep, voffA);
;       PG8_WAIT_V(6); PG8_BAR; PG8_MMA(1, 1, At, B1); PG8_BAR;
;       PG8_LDB(B0, 1, 0); PG8_SCHED; PG8_LDA(At, 1, 0); PG8_STAGE(PG8_SA(0, 1), a2 + hstep, voffA);
;       PG8_WAIT_L(8); PG8_BAR; PG8_WAIT_L(0); PG8_MMA(0, 0, At, B0); PG8_BAR; PG8_SCHED;
;       PG8_LDB(B1, 1, 1); PG8_STAGE(PG8_SB(1, 0), b3, voffA);
;       PG8_BAR; PG8_WAIT_L(0); PG8_MMA(0, 1, At, B1); PG8_BAR;
;       PG8_LDA(At, 1, 1); PG8_STAGE(PG8_SA(1, 0), a3, voffA);
;       PG8_BAR; PG8_WAIT_L(0); PG8_MMA(1, 0, At, B0); PG8_BAR; PG8_SCHED;
;       PG8_STAGE(PG8_SB(1, 1), b3 + hstep, voffA);
;       PG8_WAIT_V(6); PG8_BAR; PG8_MMA(1, 1, At, B1); PG8_BAR;
.LBB0_816:
	s_add_i32 s94, s30, 2
	s_add_u32 s52, s2, 0x80
	s_addc_u32 s31, s3, 0
	s_add_i32 s36, 0, 0x10000
	v_add_u32_e32 v141, s36, v138
	ds_read_b128 v[142:145], v141
	ds_read_b128 v[154:157], v141 offset:1024
	ds_read_b128 v[158:161], v141 offset:2048
	ds_read_b128 v[162:165], v141 offset:3072
	s_cmp_eq_u32 vcc_lo, s30
	s_cselect_b32 s30, s0, s52
	s_cselect_b32 s31, s1, s31
	s_cselect_b32 s53, s29, s97
	s_cselect_b32 s52, s28, vcc_hi
	v_lshl_add_u64 v[146:147], s[2:3], 0, v[134:135]
	s_add_i32 m0, s81, 0xc000
	ds_read_b128 v[166:169], v140
	ds_read_b128 v[170:173], v140 offset:1024
	ds_read_b128 v[204:207], v140 offset:2048
	ds_read_b128 v[208:211], v140 offset:3072
	ds_read_b128 v[212:215], v140 offset:4096
	ds_read_b128 v[216:219], v140 offset:5120
	ds_read_b128 v[220:223], v140 offset:6144
	ds_read_b128 v[224:227], v140 offset:7168
	global_load_lds_dwordx4 v[146:147], off
	v_lshl_add_u64 v[146:147], s[2:3], 0, v[136:137]
	s_add_i32 m0, s81, 0xe000
	s_nop 0
	global_load_lds_dwordx4 v[146:147], off
	s_waitcnt lgkmcnt(8)
	s_barrier
	s_waitcnt lgkmcnt(0)
	s_setprio 1
	s_waitcnt lgkmcnt(0)
	v_mfma_f32_16x16x32_bf16 v[128:131], v[142:145], v[166:169], v[128:131]
	v_mfma_f32_16x16x32_bf16 v[124:127], v[158:161], v[166:169], v[124:127]
	v_mfma_f32_16x16x32_bf16 v[120:123], v[142:145], v[204:207], v[120:123]
	v_mfma_f32_16x16x32_bf16 v[112:115], v[158:161], v[204:207], v[112:115]
	v_mfma_f32_16x16x32_bf16 v[104:107], v[142:145], v[212:215], v[104:107]
	v_mfma_f32_16x16x32_bf16 v[96:99], v[158:161], v[212:215], v[96:99]
	v_mfma_f32_16x16x32_bf16 v[88:91], v[142:145], v[220:223], v[88:91]
	v_mfma_f32_16x16x32_bf16 v[80:83], v[158:161], v[220:223], v[80:83]
	v_mfma_f32_16x16x32_bf16 v[128:131], v[154:157], v[170:173], v[128:131]
	v_mfma_f32_16x16x32_bf16 v[124:127], v[162:165], v[170:173], v[124:127]
	v_mfma_f32_16x16x32_bf16 v[120:123], v[154:157], v[208:211], v[120:123]
	v_mfma_f32_16x16x32_bf16 v[112:115], v[162:165], v[208:211], v[112:115]
	v_mfma_f32_16x16x32_bf16 v[104:107], v[154:157], v[216:219], v[104:107]
	v_mfma_f32_16x16x32_bf16 v[96:99], v[162:165], v[216:219], v[96:99]
	v_mfma_f32_16x16x32_bf16 v[88:91], v[154:157], v[224:227], v[88:91]
	v_mfma_f32_16x16x32_bf16 v[80:83], v[162:165], v[224:227], v[80:83]
	s_setprio 0
	s_barrier
	s_add_i32 s37, 0, 0x14000
	s_add_i32 s36, s36, s79
	v_add_u32_e32 v141, s37, v138
	v_lshl_add_u64 v[146:147], s[52:53], 0, v[16:17]
	s_mov_b32 m0, s36
	ds_read_b128 v[228:231], v141
	ds_read_b128 v[232:235], v141 offset:1024
	ds_read_b128 v[236:239], v141 offset:2048
	ds_read_b128 v[240:243], v141 offset:3072
	global_load_lds_dwordx4 v[146:147], off
	v_lshl_add_u64 v[244:245], s[52:53], 0, v[132:133]
	s_add_i32 m0, s36, 0x2000
	s_nop 0
	global_load_lds_dwordx4 v[244:245], off
	s_barrier
	s_waitcnt lgkmcnt(0)
	s_setprio 1
	s_waitcnt lgkmcnt(0)
	v_mfma_f32_16x16x32_bf16 v[116:119], v[228:231], v[166:169], v[116:119]
	v_mfma_f32_16x16x32_bf16 v[108:111], v[236:239], v[166:169], v[108:111]
	v_mfma_f32_16x16x32_bf16 v[100:103], v[228:231], v[204:207], v[100:103]
	v_mfma_f32_16x16x32_bf16 v[92:95], v[236:239], v[204:207], v[92:95]
	v_mfma_f32_16x16x32_bf16 v[84:87], v[228:231], v[212:215], v[84:87]
	v_mfma_f32_16x16x32_bf16 v[76:79], v[236:239], v[212:215], v[76:79]
	v_mfma_f32_16x16x32_bf16 v[72:75], v[228:231], v[220:223], v[72:75]
	v_mfma_f32_16x16x32_bf16 v[68:71], v[236:239], v[220:223], v[68:71]
	v_mfma_f32_16x16x32_bf16 v[116:119], v[232:235], v[170:173], v[116:119]
	v_mfma_f32_16x16x32_bf16 v[108:111], v[240:243], v[170:173], v[108:111]
	v_mfma_f32_16x16x32_bf16 v[100:103], v[232:235], v[208:211], v[100:103]
	v_mfma_f32_16x16x32_bf16 v[92:95], v[240:243], v[208:211], v[92:95]
	v_mfma_f32_16x16x32_bf16 v[84:87], v[232:235], v[216:219], v[84:87]
	v_mfma_f32_16x16x32_bf16 v[76:79], v[240:243], v[216:219], v[76:79]
	v_mfma_f32_16x16x32_bf16 v[72:75], v[232:235], v[224:227], v[72:75]
	v_mfma_f32_16x16x32_bf16 v[68:71], v[240:243], v[224:227], v[68:71]
	s_setprio 0
	s_mov_b32 m0, s81
	v_lshl_add_u64 v[246:247], s[30:31], 0, v[16:17]
	s_barrier
	ds_read_b128 v[166:169], v140 offset:16384
	ds_read_b128 v[170:173], v140 offset:17408
	ds_read_b128 v[204:207], v140 offset:18432
	ds_read_b128 v[208:211], v140 offset:19456
	ds_read_b128 v[212:215], v140 offset:20480
	ds_read_b128 v[216:219], v140 offset:21504
	ds_read_b128 v[220:223], v140 offset:22528
	ds_read_b128 v[224:227], v140 offset:23552
	global_load_lds_dwordx4 v[246:247], off
	v_lshl_add_u64 v[248:249], s[30:31], 0, v[132:133]
	s_mov_b32 m0, s82
	s_nop 0
	global_load_lds_dwordx4 v[248:249], off
	s_barrier
	s_waitcnt lgkmcnt(0)
	s_setprio 1
	s_waitcnt lgkmcnt(0)
	v_mfma_f32_16x16x32_bf16 v[64:67], v[142:145], v[166:169], v[64:67]
	v_mfma_f32_16x16x32_bf16 v[60:63], v[158:161], v[166:169], v[60:63]
	v_mfma_f32_16x16x32_bf16 v[56:59], v[142:145], v[204:207], v[56:59]
	v_mfma_f32_16x16x32_bf16 v[52:55], v[158:161], v[204:207], v[52:55]
	v_mfma_f32_16x16x32_bf16 v[40:43], v[142:145], v[212:215], v[40:43]
	v_mfma_f32_16x16x32_bf16 v[36:39], v[158:161], v[212:215], v[36:39]
	v_mfma_f32_16x16x32_bf16 v[24:27], v[142:145], v[220:223], v[24:27]
	v_mfma_f32_16x16x32_bf16 v[20:23], v[158:161], v[220:223], v[20:23]
	v_mfma_f32_16x16x32_bf16 v[64:67], v[154:157], v[170:173], v[64:67]
	v_mfma_f32_16x16x32_bf16 v[60:63], v[162:165], v[170:173], v[60:63]
	v_mfma_f32_16x16x32_bf16 v[56:59], v[154:157], v[208:211], v[56:59]
	v_mfma_f32_16x16x32_bf16 v[52:55], v[162:165], v[208:211], v[52:55]
	v_mfma_f32_16x16x32_bf16 v[40:43], v[154:157], v[216:219], v[40:43]
	v_mfma_f32_16x16x32_bf16 v[36:39], v[162:165], v[216:219], v[36:39]
	v_mfma_f32_16x16x32_bf16 v[24:27], v[154:157], v[224:227], v[24:27]
	v_mfma_f32_16x16x32_bf16 v[20:23], v[162:165], v[224:227], v[20:23]
	s_setprio 0
	s_barrier
; #define PG8_STAGE(bufoff, gbase, voff) do { _Pragma("unroll") for (int _i = 0; _i < 2; ++_i) \
;         __builtin_amdgcn_global_load_lds((const unsigned*)((const char*)(gbase) + (voff)[_i]), (LAS unsigned*)(lds + (bufoff) + ldsw + _i * 8192), 16, 0, 0); } while (0)
; #define PG8_LDA(dst, b, h) do { _Pragma("unroll") for (int m = 0; m < 4; ++m) _Pragma("unroll") for (int k = 0; k < 2; ++k) dst[m][k] = *(const LAS bf16x8*)(lds + PG8_SA(b, h) + aoff + m * 2048 + k * 1024); } while (0)
; #define PG8_LDB(dst, b, h) do { _Pragma("unroll") for (int n = 0; n < 2; ++n) _Pragma("unroll") for (int k = 0; k < 2; ++k) dst[n][k] = *(const LAS bf16x8*)(lds + PG8_SB(b, h) + boff + n * 2048 + k * 1024); } while (0)
; #define PG8_BAR __builtin_amdgcn_s_barrier()
; template <class Epi>
; __device__ __forceinline__ void gemm_phase(const int tid, LAS unsigned char* lds, const Gemm g, const StaticOrder& S, const Epi& E) {
;     ...
;     for (int t = 0; t < nt; t += 2) {
;       const bool last = (t == nt - 2);
;       const char* a1 = cA + (size_t)(t + 1) * kstep;
;       const char* a2 = last ? nA : cA + (size_t)(t + 2) * kstep; const char* b2 = last ? nB : cB + (size_t)(t + 2) * kstep;
;       const char* a3 = a2 + kstep; const char* b3 = b2 + kstep;
;       PG8_LDB(B0, 0, 0); PG8_SCHED; PG8_LDA(At, 0, 0); PG8_STAGE(PG8_SA(1, 1), a1 + hstep, voffA);
;       PG8_WAIT_L(8); PG8_BAR; PG8_WAIT_L(0); PG8_MMA(0, 0, At, B0); PG8_BAR; PG8_SCHED;
;       PG8_LDB(B1, 0, 1); PG8_STAGE(PG8_SB(0, 0), b2, voffA);
;       PG8_BAR; PG8_WAIT_L(0); PG8_MMA(0, 1, At, B1); PG8_BAR;
;       PG8_LDA(At, 0, 1); PG8_STAGE(PG8_SA(0, 0), a2, voffA);
;       PG8_BAR; PG8_WAIT_L(0); PG8_MMA(1, 0, At, B0); PG8_BAR; PG8_SCHED;
;       PG8_STAGE(PG8_SB(0, 1), b2 + hstep, voffA);
;       PG8_WAIT_V(6); PG8_BAR; PG8_MMA(1, 1, At, B1); PG8_BAR;
;       PG8_LDB(B0, 1, 0); PG8_SCHED; PG8_LDA(At, 1, 0); PG8_STAGE(PG8_SA(0, 1), a2 + hstep, voffA);
;       PG8_WAIT_L(8); PG8_BAR; PG8_WAIT_L(0); PG8_MMA(0, 0, At, B0); PG8_BAR; PG8_SCHED;
;       PG8_LDB(B1, 1, 1); PG8_STAGE(PG8_SB(1, 0), b3, voffA);
;       PG8_BAR; PG8_WAIT_L(0); PG8_MMA(0, 1, At, B1); PG8_BAR;
;       PG8_LDA(At, 1, 1); PG8_STAGE(PG8_SA(1, 0), a3, voffA);
;       PG8_BAR; PG8_WAIT_L(0); PG8_MMA(1, 0, At, B0); PG8_BAR; PG8_SCHED;
;       PG8_STAGE(PG8_SB(1, 1), b3 + hstep, voffA);
;       PG8_WAIT_V(6); PG8_BAR; PG8_MMA(1, 1, At, B1); PG8_BAR;
	s_add_u32 s52, s52, s92
	s_addc_u32 s53, s53, 0
	s_add_i32 s36, s37, s79
	v_lshl_add_u64 v[250:251], s[52:53], 0, v[16:17]
	s_mov_b32 m0, s36
	v_lshl_add_u64 v[148:149], s[52:53], 0, v[132:133]
	global_load_lds_dwordx4 v[250:251], off
	s_add_i32 m0, s36, 0x2000
	s_nop 0
	global_load_lds_dwordx4 v[148:149], off
	s_waitcnt vmcnt(6)
	s_barrier
	s_setprio 1
	v_mfma_f32_16x16x32_bf16 v[48:51], v[228:231], v[166:169], v[48:51]
	v_mfma_f32_16x16x32_bf16 v[44:47], v[236:239], v[166:169], v[44:47]
	v_mfma_f32_16x16x32_bf16 v[32:35], v[228:231], v[204:207], v[32:35]
	v_mfma_f32_16x16x32_bf16 v[28:31], v[236:239], v[204:207], v[28:31]
	v_mfma_f32_16x16x32_bf16 v[12:15], v[228:231], v[212:215], v[12:15]
	v_mfma_f32_16x16x32_bf16 v[8:11], v[236:239], v[212:215], v[8:11]
	v_mfma_f32_16x16x32_bf16 v[4:7], v[228:231], v[220:223], v[4:7]
	v_mfma_f32_16x16x32_bf16 v[0:3], v[236:239], v[220:223], v[0:3]
	v_mfma_f32_16x16x32_bf16 v[48:51], v[232:235], v[170:173], v[48:51]
	v_mfma_f32_16x16x32_bf16 v[44:47], v[240:243], v[170:173], v[44:47]
	v_mfma_f32_16x16x32_bf16 v[32:35], v[232:235], v[208:211], v[32:35]
	v_mfma_f32_16x16x32_bf16 v[28:31], v[240:243], v[208:211], v[28:31]
	v_mfma_f32_16x16x32_bf16 v[12:15], v[232:235], v[216:219], v[12:15]
	v_mfma_f32_16x16x32_bf16 v[8:11], v[240:243], v[216:219], v[8:11]
	v_mfma_f32_16x16x32_bf16 v[4:7], v[232:235], v[224:227], v[4:7]
	v_mfma_f32_16x16x32_bf16 v[0:3], v[240:243], v[224:227], v[0:3]
	s_setprio 0
	s_add_i32 s36, 0, 0x18000
	v_add_u32_e32 v141, s36, v138
	s_barrier
	ds_read_b128 v[142:145], v141
	ds_read_b128 v[154:157], v141 offset:1024
	ds_read_b128 v[158:161], v141 offset:2048
	ds_read_b128 v[162:165], v141 offset:3072
	s_add_u32 s30, s30, s92
	s_addc_u32 s31, s31, 0
	s_mov_b32 m0, s83
	v_lshl_add_u64 v[228:229], s[30:31], 0, v[16:17]
	ds_read_b128 v[166:169], v140 offset:32768
	ds_read_b128 v[170:173], v140 offset:33792
	ds_read_b128 v[204:207], v140 offset:34816
	ds_read_b128 v[208:211], v140 offset:35840
	ds_read_b128 v[212:215], v140 offset:36864
	ds_read_b128 v[216:219], v140 offset:37888
	ds_read_b128 v[220:223], v140 offset:38912
	ds_read_b128 v[224:227], v140 offset:39936
	global_load_lds_dwordx4 v[228:229], off
	v_lshl_add_u64 v[228:229], s[30:31], 0, v[132:133]
	s_mov_b32 m0, s84
	s_nop 0
	global_load_lds_dwordx4 v[228:229], off
	s_waitcnt lgkmcnt(8)
	s_barrier
	s_waitcnt lgkmcnt(0)
	s_setprio 1
	s_waitcnt lgkmcnt(0)
	v_mfma_f32_16x16x32_bf16 v[128:131], v[142:145], v[166:169], v[128:131]
	v_mfma_f32_16x16x32_bf16 v[124:127], v[158:161], v[166:169], v[124:127]
	v_mfma_f32_16x16x32_bf16 v[120:123], v[142:145], v[204:207], v[120:123]
	v_mfma_f32_16x16x32_bf16 v[112:115], v[158:161], v[204:207], v[112:115]
	v_mfma_f32_16x16x32_bf16 v[104:107], v[142:145], v[212:215], v[104:107]
	v_mfma_f32_16x16x32_bf16 v[96:99], v[158:161], v[212:215], v[96:99]
	v_mfma_f32_16x16x32_bf16 v[88:91], v[142:145], v[220:223], v[88:91]
	v_mfma_f32_16x16x32_bf16 v[80:83], v[158:161], v[220:223], v[80:83]
	v_mfma_f32_16x16x32_bf16 v[128:131], v[154:157], v[170:173], v[128:131]
	v_mfma_f32_16x16x32_bf16 v[124:127], v[162:165], v[170:173], v[124:127]
	v_mfma_f32_16x16x32_bf16 v[120:123], v[154:157], v[208:211], v[120:123]
	v_mfma_f32_16x16x32_bf16 v[112:115], v[162:165], v[208:211], v[112:115]
	v_mfma_f32_16x16x32_bf16 v[104:107], v[154:157], v[216:219], v[104:107]
	v_mfma_f32_16x16x32_bf16 v[96:99], v[162:165], v[216:219], v[96:99]
	v_mfma_f32_16x16x32_bf16 v[88:91], v[154:157], v[224:227], v[88:91]
	v_mfma_f32_16x16x32_bf16 v[80:83], v[162:165], v[224:227], v[80:83]
	s_setprio 0
	s_barrier
	s_add_i32 s30, 0, 0x1c000
	s_add_i32 s31, s36, s79
	v_add_u32_e32 v141, s30, v138
	v_lshl_add_u64 v[146:147], v[146:147], 0, s[4:5]
	s_mov_b32 m0, s31
	ds_read_b128 v[228:231], v141
	ds_read_b128 v[232:235], v141 offset:1024
	ds_read_b128 v[236:239], v141 offset:2048
	ds_read_b128 v[240:243], v141 offset:3072
	global_load_lds_dwordx4 v[146:147], off
	v_lshl_add_u64 v[146:147], v[244:245], 0, s[4:5]
	s_add_i32 m0, s31, 0x2000
	s_nop 0
	global_load_lds_dwordx4 v[146:147], off
	s_barrier
	s_waitcnt lgkmcnt(0)
	s_setprio 1
	s_waitcnt lgkmcnt(0)
	v_mfma_f32_16x16x32_bf16 v[116:119], v[228:231], v[166:169], v[116:119]
	v_mfma_f32_16x16x32_bf16 v[108:111], v[236:239], v[166:169], v[108:111]
	v_mfma_f32_16x16x32_bf16 v[100:103], v[228:231], v[204:207], v[100:103]
	v_mfma_f32_16x16x32_bf16 v[92:95], v[236:239], v[204:207], v[92:95]
	v_mfma_f32_16x16x32_bf16 v[84:87], v[228:231], v[212:215], v[84:87]
	v_mfma_f32_16x16x32_bf16 v[76:79], v[236:239], v[212:215], v[76:79]
	v_mfma_f32_16x16x32_bf16 v[72:75], v[228:231], v[220:223], v[72:75]
	v_mfma_f32_16x16x32_bf16 v[68:71], v[236:239], v[220:223], v[68:71]
	v_mfma_f32_16x16x32_bf16 v[116:119], v[232:235], v[170:173], v[116:119]
	v_mfma_f32_16x16x32_bf16 v[108:111], v[240:243], v[170:173], v[108:111]
	v_mfma_f32_16x16x32_bf16 v[100:103], v[232:235], v[208:211], v[100:103]
	v_mfma_f32_16x16x32_bf16 v[92:95], v[240:243], v[208:211], v[92:95]
	v_mfma_f32_16x16x32_bf16 v[84:87], v[232:235], v[216:219], v[84:87]
	v_mfma_f32_16x16x32_bf16 v[76:79], v[240:243], v[216:219], v[76:79]
	v_mfma_f32_16x16x32_bf16 v[72:75], v[232:235], v[224:227], v[72:75]
	v_mfma_f32_16x16x32_bf16 v[68:71], v[240:243], v[224:227], v[68:71]
	s_setprio 0
	s_mov_b32 m0, s86
	v_lshl_add_u64 v[146:147], v[246:247], 0, s[4:5]
	s_barrier
	ds_read_b128 v[166:169], v140 offset:49152
	ds_read_b128 v[170:173], v140 offset:50176
	ds_read_b128 v[204:207], v140 offset:51200
	ds_read_b128 v[208:211], v140 offset:52224
	ds_read_b128 v[212:215], v140 offset:53248
	ds_read_b128 v[216:219], v140 offset:54272
	ds_read_b128 v[220:223], v140 offset:55296
	ds_read_b128 v[224:227], v140 offset:56320
	global_load_lds_dwordx4 v[146:147], off
	v_lshl_add_u64 v[146:147], v[248:249], 0, s[4:5]
	s_mov_b32 m0, s44
	s_nop 0
	global_load_lds_dwordx4 v[146:147], off
	s_barrier
; #define PG8_STAGE(bufoff, gbase, voff) do { _Pragma("unroll") for (int _i = 0; _i < 2; ++_i) \
;         __builtin_amdgcn_global_load_lds((const unsigned*)((const char*)(gbase) + (voff)[_i]), (LAS unsigned*)(lds + (bufoff) + ldsw + _i * 8192), 16, 0, 0); } while (0)
; #define PG8_LDA(dst, b, h) do { _Pragma("unroll") for (int m = 0; m < 4; ++m) _Pragma("unroll") for (int k = 0; k < 2; ++k) dst[m][k] = *(const LAS bf16x8*)(lds + PG8_SA(b, h) + aoff + m * 2048 + k * 1024); } while (0)
; #define PG8_LDB(dst, b, h) do { _Pragma("unroll") for (int n = 0; n < 2; ++n) _Pragma("unroll") for (int k = 0; k < 2; ++k) dst[n][k] = *(const LAS bf16x8*)(lds + PG8_SB(b, h) + boff + n * 2048 + k * 1024); } while (0)
; #define PG8_MMA(ai, bj, At, Bt) do { __builtin_amdgcn_s_setprio(1); _Pragma("unroll") for (int m = 0; m < 4; ++m) _Pragma("unroll") for (int n = 0; n < 2; ++n) _Pragma("unroll") for (int k = 0; k < 2; ++k) \
;         acc[ai][bj][m][n] = __builtin_amdgcn_mfma_f32_16x16x32_bf16(Bt[n][k], At[m][k], acc[ai][bj][m][n], 0, 0, 0); __builtin_amdgcn_s_setprio(0); } while (0)
; #define PG8_WAIT_V(n) asm volatile("s_waitcnt vmcnt(" #n ")" ::: "memory")
; #define PG8_WAIT_L(n) asm volatile("s_waitcnt lgkmcnt(" #n ")" ::: "memory")
; #define PG8_BAR __builtin_amdgcn_s_barrier()
; #define PG8_SCHED __builtin_amdgcn_sched_barrier(0)
; template <class Epi>
; __device__ __forceinline__ void gemm_phase(const int tid, LAS unsigned char* lds, const Gemm g, const StaticOrder& S, const Epi& E) {
;     ...
;       PG8_WAIT_V(6); PG8_BAR; PG8_MMA(1, 1, At, B1); PG8_BAR;
;       PG8_LDB(B0, 1, 0); PG8_SCHED; PG8_LDA(At, 1, 0); PG8_STAGE(PG8_SA(0, 1), a2 + hstep, voffA);
;       PG8_WAIT_L(8); PG8_BAR; PG8_WAIT_L(0); PG8_MMA(0, 0, At, B0); PG8_BAR; PG8_SCHED;
;       PG8_LDB(B1, 1, 1); PG8_STAGE(PG8_SB(1, 0), b3, voffA);
;       PG8_BAR; PG8_WAIT_L(0); PG8_MMA(0, 1, At, B1); PG8_BAR;
;       PG8_LDA(At, 1, 1); PG8_STAGE(PG8_SA(1, 0), a3, voffA);
;       PG8_BAR; PG8_WAIT_L(0); PG8_MMA(1, 0, At, B0); PG8_BAR; PG8_SCHED;
;       PG8_STAGE(PG8_SB(1, 1), b3 + hstep, voffA);
;       PG8_WAIT_V(6); PG8_BAR; PG8_MMA(1, 1, At, B1); PG8_BAR;
	s_waitcnt lgkmcnt(0)
	s_setprio 1
	s_waitcnt lgkmcnt(0)
	v_mfma_f32_16x16x32_bf16 v[64:67], v[142:145], v[166:169], v[64:67]
	v_mfma_f32_16x16x32_bf16 v[60:63], v[158:161], v[166:169], v[60:63]
	v_mfma_f32_16x16x32_bf16 v[56:59], v[142:145], v[204:207], v[56:59]
	v_mfma_f32_16x16x32_bf16 v[52:55], v[158:161], v[204:207], v[52:55]
	v_mfma_f32_16x16x32_bf16 v[40:43], v[142:145], v[212:215], v[40:43]
	v_mfma_f32_16x16x32_bf16 v[36:39], v[158:161], v[212:215], v[36:39]
	v_mfma_f32_16x16x32_bf16 v[24:27], v[142:145], v[220:223], v[24:27]
	v_mfma_f32_16x16x32_bf16 v[20:23], v[158:161], v[220:223], v[20:23]
	v_mfma_f32_16x16x32_bf16 v[64:67], v[154:157], v[170:173], v[64:67]
	v_mfma_f32_16x16x32_bf16 v[60:63], v[162:165], v[170:173], v[60:63]
	v_mfma_f32_16x16x32_bf16 v[56:59], v[154:157], v[208:211], v[56:59]
	v_mfma_f32_16x16x32_bf16 v[52:55], v[162:165], v[208:211], v[52:55]
	v_mfma_f32_16x16x32_bf16 v[40:43], v[154:157], v[216:219], v[40:43]
	v_mfma_f32_16x16x32_bf16 v[36:39], v[162:165], v[216:219], v[36:39]
	v_mfma_f32_16x16x32_bf16 v[24:27], v[154:157], v[224:227], v[24:27]
	v_mfma_f32_16x16x32_bf16 v[20:23], v[162:165], v[224:227], v[20:23]
	s_setprio 0
	s_barrier
	s_add_i32 s30, s30, s79
	v_lshl_add_u64 v[142:143], v[250:251], 0, s[4:5]
	s_mov_b32 m0, s30
	s_nop 0
	global_load_lds_dwordx4 v[142:143], off
	v_lshl_add_u64 v[142:143], v[148:149], 0, s[4:5]
	s_add_i32 m0, s30, 0x2000
	s_nop 0
	global_load_lds_dwordx4 v[142:143], off
	s_waitcnt vmcnt(6)
	s_barrier
	s_setprio 1
	v_mfma_f32_16x16x32_bf16 v[48:51], v[228:231], v[166:169], v[48:51]
	v_mfma_f32_16x16x32_bf16 v[44:47], v[236:239], v[166:169], v[44:47]
	v_mfma_f32_16x16x32_bf16 v[32:35], v[228:231], v[204:207], v[32:35]
	v_mfma_f32_16x16x32_bf16 v[28:31], v[236:239], v[204:207], v[28:31]
	v_mfma_f32_16x16x32_bf16 v[12:15], v[228:231], v[212:215], v[12:15]
	v_mfma_f32_16x16x32_bf16 v[8:11], v[236:239], v[212:215], v[8:11]
	v_mfma_f32_16x16x32_bf16 v[4:7], v[228:231], v[220:223], v[4:7]
	v_mfma_f32_16x16x32_bf16 v[0:3], v[236:239], v[220:223], v[0:3]
	v_mfma_f32_16x16x32_bf16 v[48:51], v[232:235], v[170:173], v[48:51]
	v_mfma_f32_16x16x32_bf16 v[44:47], v[240:243], v[170:173], v[44:47]
	v_mfma_f32_16x16x32_bf16 v[32:35], v[232:235], v[208:211], v[32:35]
	v_mfma_f32_16x16x32_bf16 v[28:31], v[240:243], v[208:211], v[28:31]
	v_mfma_f32_16x16x32_bf16 v[12:15], v[232:235], v[216:219], v[12:15]
	v_mfma_f32_16x16x32_bf16 v[8:11], v[240:243], v[216:219], v[8:11]
	v_mfma_f32_16x16x32_bf16 v[4:7], v[232:235], v[224:227], v[4:7]
	v_mfma_f32_16x16x32_bf16 v[0:3], v[240:243], v[224:227], v[0:3]
	s_setprio 0
	s_add_u32 s2, s2, 0x100
	s_addc_u32 s3, s3, 0
	s_add_u32 vcc_hi, vcc_hi, 0x100
	s_addc_u32 s97, s97, 0
	s_cmp_ge_u32 s94, s20
	s_mov_b32 s30, s94
	s_barrier
	s_cbranch_scc0 .LBB0_816
;   __device__ __forceinline__ void operator()(const f32x4 (&acc)[2][2][4][2], const Unit& u, int wr, int wc, int fr, int fq) const {
;     const int row0 = u.pm * BM + wr * 64 + fr, col0 = u.pn * BM + wc * 32 + 4 * fq;
;     bfu* Cb = C + (size_t)u.ks * part_stride;
; #pragma unroll
;     for (int ai = 0; ai < 2; ++ai)
; #pragma unroll
;       for (int m = 0; m < 4; ++m) {
;         bfu* rowp = Cb + (size_t)(row0 + ai * HALF + m * 16) * ldc + col0;
; #pragma unroll
;         for (int bj = 0; bj < 2; ++bj)
; #pragma unroll
;           for (int n = 0; n < 2; ++n) {
;             const f32x4 v = acc[ai][bj][m][n];
;             uint2 o; o.x = pack2(v[0], v[1]); o.y = pack2(v[2], v[3]);
;             *reinterpret_cast<uint2*>(rowp + bj * HALF + n * 16) = o;
;           }
;       }
;   }
	v_lshl_or_b32 v142, s21, 8, v139
	s_mul_i32 s2, s85, 0x2400000
	v_readlane_b32 s20, v252, 8
	s_mul_hi_i32 s3, s85, 0x2400000
	v_readlane_b32 s21, v252, 9
	s_add_u32 s2, s20, s2
	v_lshl_add_u32 v144, s87, 8, v19
	s_addc_u32 s3, s21, s3
	v_ashrrev_i32_e32 v143, 31, v142
	v_ashrrev_i32_e32 v145, 31, v144
	v_lshl_add_u64 v[142:143], v[142:143], 1, s[2:3]
	v_lshlrev_b64 v[146:147], 12, v[144:145]
	v_lshl_add_u64 v[146:147], v[142:143], 0, v[146:147]
	v_and_b32_e32 v142, 4, v139
	v_mul_u32_u24_e32 v142, 6, v142
	v_mov_b32_e32 v143, 0
	v_lshl_add_u64 v[146:147], v[146:147], 0, v[142:143]
	v_cvt_pk_bf16_f32 v128, v128, v129
	v_cvt_pk_bf16_f32 v129, v130, v131
	v_cvt_pk_bf16_f32 v130, v124, v125
	v_cvt_pk_bf16_f32 v131, v126, v127
	v_cvt_pk_bf16_f32 v116, v116, v117
	v_cvt_pk_bf16_f32 v117, v118, v119
	v_cvt_pk_bf16_f32 v118, v108, v109
	v_cvt_pk_bf16_f32 v119, v110, v111
	s_nop 1
	v_permlane16_swap_b32_e32 v128, v130
	v_permlane16_swap_b32_e32 v129, v131
	v_permlane16_swap_b32_e32 v116, v118
	v_permlane16_swap_b32_e32 v117, v119
	global_store_dwordx4 v[146:147], v[128:131], off
	global_store_dwordx4 v[146:147], v[116:119], off offset:256
	s_mov_b64 s[2:3], 0x10000
	v_lshl_add_u64 v[144:145], v[146:147], 0, s[2:3]
	v_cvt_pk_bf16_f32 v120, v120, v121
	v_cvt_pk_bf16_f32 v121, v122, v123
	v_cvt_pk_bf16_f32 v122, v112, v113
	v_cvt_pk_bf16_f32 v123, v114, v115
	v_cvt_pk_bf16_f32 v100, v100, v101
	v_cvt_pk_bf16_f32 v101, v102, v103
	v_cvt_pk_bf16_f32 v102, v92, v93
	v_cvt_pk_bf16_f32 v103, v94, v95
	s_nop 1
	v_permlane16_swap_b32_e32 v120, v122
	v_permlane16_swap_b32_e32 v121, v123
	v_permlane16_swap_b32_e32 v100, v102
	v_permlane16_swap_b32_e32 v101, v103
	global_store_dwordx4 v[144:145], v[120:123], off
	global_store_dwordx4 v[144:145], v[100:103], off offset:256
	s_mov_b64 s[2:3], 0x20000
	v_lshl_add_u64 v[144:145], v[146:147], 0, s[2:3]
	v_cvt_pk_bf16_f32 v104, v104, v105
	v_cvt_pk_bf16_f32 v105, v106, v107
	v_cvt_pk_bf16_f32 v106, v96, v97
	v_cvt_pk_bf16_f32 v107, v98, v99
	v_cvt_pk_bf16_f32 v84, v84, v85
	v_cvt_pk_bf16_f32 v85, v86, v87
	v_cvt_pk_bf16_f32 v86, v76, v77
	v_cvt_pk_bf16_f32 v87, v78, v79
	s_nop 1
	v_permlane16_swap_b32_e32 v104, v106
	v_permlane16_swap_b32_e32 v105, v107
	v_permlane16_swap_b32_e32 v84, v86
	v_permlane16_swap_b32_e32 v85, v87
	global_store_dwordx4 v[144:145], v[104:107], off
	global_store_dwordx4 v[144:145], v[84:87], off offset:256
	s_mov_b64 s[2:3], 0x30000
	v_lshl_add_u64 v[144:145], v[146:147], 0, s[2:3]
	v_cvt_pk_bf16_f32 v88, v88, v89
	v_cvt_pk_bf16_f32 v89, v90, v91
	v_cvt_pk_bf16_f32 v90, v80, v81
	v_cvt_pk_bf16_f32 v91, v82, v83
	v_cvt_pk_bf16_f32 v72, v72, v73
	v_cvt_pk_bf16_f32 v73, v74, v75
	v_cvt_pk_bf16_f32 v74, v68, v69
	v_cvt_pk_bf16_f32 v75, v70, v71
	s_nop 1
	v_permlane16_swap_b32_e32 v88, v90
	v_permlane16_swap_b32_e32 v89, v91
	v_permlane16_swap_b32_e32 v72, v74
	v_permlane16_swap_b32_e32 v73, v75
	global_store_dwordx4 v[144:145], v[88:91], off
	global_store_dwordx4 v[144:145], v[72:75], off offset:256
	s_mov_b64 s[2:3], 0x80000
	v_lshl_add_u64 v[144:145], v[146:147], 0, s[2:3]
	v_cvt_pk_bf16_f32 v64, v64, v65
	v_cvt_pk_bf16_f32 v65, v66, v67
	v_cvt_pk_bf16_f32 v66, v60, v61
	v_cvt_pk_bf16_f32 v67, v62, v63
	v_cvt_pk_bf16_f32 v48, v48, v49
	v_cvt_pk_bf16_f32 v49, v50, v51
	v_cvt_pk_bf16_f32 v50, v44, v45
	v_cvt_pk_bf16_f32 v51, v46, v47
	s_nop 1
	v_permlane16_swap_b32_e32 v64, v66
	v_permlane16_swap_b32_e32 v65, v67
	v_permlane16_swap_b32_e32 v48, v50
	v_permlane16_swap_b32_e32 v49, v51
	global_store_dwordx4 v[144:145], v[64:67], off
	global_store_dwordx4 v[144:145], v[48:51], off offset:256
	s_mov_b64 s[2:3], 0x90000
	v_lshl_add_u64 v[144:145], v[146:147], 0, s[2:3]
	v_cvt_pk_bf16_f32 v56, v56, v57
	v_cvt_pk_bf16_f32 v57, v58, v59
	v_cvt_pk_bf16_f32 v58, v52, v53
	v_cvt_pk_bf16_f32 v59, v54, v55
	v_cvt_pk_bf16_f32 v32, v32, v33
	v_cvt_pk_bf16_f32 v33, v34, v35
	v_cvt_pk_bf16_f32 v34, v28, v29
	v_cvt_pk_bf16_f32 v35, v30, v31
	s_nop 1
	v_permlane16_swap_b32_e32 v56, v58
	v_permlane16_swap_b32_e32 v57, v59
	v_permlane16_swap_b32_e32 v32, v34
	v_permlane16_swap_b32_e32 v33, v35
	global_store_dwordx4 v[144:145], v[56:59], off
	global_store_dwordx4 v[144:145], v[32:35], off offset:256
	s_mov_b64 s[2:3], 0xa0000
	v_lshl_add_u64 v[144:145], v[146:147], 0, s[2:3]
	v_cvt_pk_bf16_f32 v40, v40, v41
	v_cvt_pk_bf16_f32 v41, v42, v43
	v_cvt_pk_bf16_f32 v42, v36, v37
	v_cvt_pk_bf16_f32 v43, v38, v39
	v_cvt_pk_bf16_f32 v12, v12, v13
	v_cvt_pk_bf16_f32 v13, v14, v15
	v_cvt_pk_bf16_f32 v14, v8, v9
	v_cvt_pk_bf16_f32 v15, v10, v11
	s_nop 1
	v_permlane16_swap_b32_e32 v40, v42
	v_permlane16_swap_b32_e32 v41, v43
	v_permlane16_swap_b32_e32 v12, v14
	v_permlane16_swap_b32_e32 v13, v15
	global_store_dwordx4 v[144:145], v[40:43], off
	global_store_dwordx4 v[144:145], v[12:15], off offset:256
	s_mov_b64 s[2:3], 0xb0000
	v_lshl_add_u64 v[144:145], v[146:147], 0, s[2:3]
	v_cvt_pk_bf16_f32 v24, v24, v25
	v_cvt_pk_bf16_f32 v25, v26, v27
	v_cvt_pk_bf16_f32 v26, v20, v21
	v_cvt_pk_bf16_f32 v27, v22, v23
	v_cvt_pk_bf16_f32 v4, v4, v5
	v_cvt_pk_bf16_f32 v5, v6, v7
	v_cvt_pk_bf16_f32 v6, v0, v1
	v_cvt_pk_bf16_f32 v7, v2, v3
	s_nop 1
	v_permlane16_swap_b32_e32 v24, v26
	v_permlane16_swap_b32_e32 v25, v27
	v_permlane16_swap_b32_e32 v4, v6
	v_permlane16_swap_b32_e32 v5, v7
	global_store_dwordx4 v[144:145], v[24:27], off
	global_store_dwordx4 v[144:145], v[4:7], off offset:256
	s_nop 1
	s_and_b64 vcc, exec, s[40:41]
	s_mov_b64 s[2:3], -1
	s_cbranch_vccnz .LBB0_807
	s_cmp_eq_u32 s75, 0
	s_cselect_b32 s20, s10, s11
	s_mov_b64 s[2:3], 0
	s_branch .LBB0_807

; #define PG8_STAGE(bufoff, gbase, voff) do { _Pragma("unroll") for (int _i = 0; _i < 2; ++_i) \
;         __builtin_amdgcn_global_load_lds((const unsigned*)((const char*)(gbase) + (voff)[_i]), (LAS unsigned*)(lds + (bufoff) + ldsw + _i * 8192), 16, 0, 0); } while (0)
; #define PG8_LDA(dst, b, h) do { _Pragma("unroll") for (int m = 0; m < 4; ++m) _Pragma("unroll") for (int k = 0; k < 2; ++k) dst[m][k] = *(const LAS bf16x8*)(lds + PG8_SA(b, h) + aoff + m * 2048 + k * 1024); } while (0)
; #define PG8_LDB(dst, b, h) do { _Pragma("unroll") for (int n = 0; n < 2; ++n) _Pragma("unroll") for (int k = 0; k < 2; ++k) dst[n][k] = *(const LAS bf16x8*)(lds + PG8_SB(b, h) + boff + n * 2048 + k * 1024); } while (0)
; #define PG8_BAR __builtin_amdgcn_s_barrier()
; template <class Epi>
; __device__ __forceinline__ void gemm_phase(const int tid, LAS unsigned char* lds, const Gemm g, const StaticOrder& S, const Epi& E) {
;     ...
;     for (int t = 0; t < nt; t += 2) {
;       const bool last = (t == nt - 2);
;       const char* a1 = cA + (size_t)(t + 1) * kstep;
;       const char* a2 = last ? nA : cA + (size_t)(t + 2) * kstep; const char* b2 = last ? nB : cB + (size_t)(t + 2) * kstep;
;       const char* a3 = a2 + kstep; const char* b3 = b2 + kstep;
;       PG8_LDB(B0, 0, 0); PG8_SCHED; PG8_LDA(At, 0, 0); PG8_STAGE(PG8_SA(1, 1), a1 + hstep, voffA);
;       PG8_WAIT_L(8); PG8_BAR; PG8_WAIT_L(0); PG8_MMA(0, 0, At, B0); PG8_BAR; PG8_SCHED;
;       PG8_LDB(B1, 0, 1); PG8_STAGE(PG8_SB(0, 0), b2, voffA);
;       PG8_BAR; PG8_WAIT_L(0); PG8_MMA(0, 1, At, B1); PG8_BAR;
;       PG8_LDA(At, 0, 1); PG8_STAGE(PG8_SA(0, 0), a2, voffA);
;       PG8_BAR; PG8_WAIT_L(0); PG8_MMA(1, 0, At, B0); PG8_BAR; PG8_SCHED;
;       PG8_STAGE(PG8_SB(0, 1), b2 + hstep, voffA);
;       PG8_WAIT_V(6); PG8_BAR; PG8_MMA(1, 1, At, B1); PG8_BAR;
;       PG8_LDB(B0, 1, 0); PG8_SCHED; PG8_LDA(At, 1, 0); PG8_STAGE(PG8_SA(0, 1), a2 + hstep, voffA);
;       PG8_WAIT_L(8); PG8_BAR; PG8_WAIT_L(0); PG8_MMA(0, 0, At, B0); PG8_BAR; PG8_SCHED;
;       PG8_LDB(B1, 1, 1); PG8_STAGE(PG8_SB(1, 0), b3, voffA);
;       PG8_BAR; PG8_WAIT_L(0); PG8_MMA(0, 1, At, B1); PG8_BAR;
;       PG8_LDA(At, 1, 1); PG8_STAGE(PG8_SA(1, 0), a3, voffA);
;       PG8_BAR; PG8_WAIT_L(0); PG8_MMA(1, 0, At, B0); PG8_BAR; PG8_SCHED;
;       PG8_STAGE(PG8_SB(1, 1), b3 + hstep, voffA);
;       PG8_WAIT_V(6); PG8_BAR; PG8_MMA(1, 1, At, B1); PG8_BAR;
.LBB0_847:
	s_add_u32 s30, s2, 0x100
	s_addc_u32 s31, s3, 0
	s_add_i32 s94, 0, 0x10000
	v_add_u32_e32 v138, s94, v140
	ds_read_b128 v[144:147], v138
	ds_read_b128 v[154:157], v138 offset:1024
	ds_read_b128 v[158:161], v138 offset:2048
	ds_read_b128 v[162:165], v138 offset:3072
	s_cmp_eq_u32 s13, 28
	s_cselect_b32 s1, s11, s31
	s_cselect_b32 s0, s20, s30
	s_cselect_b32 vcc_hi, s21, s12
	s_cselect_b32 vcc_lo, s29, s45
	v_lshl_add_u64 v[138:139], s[2:3], 0, v[134:135]
	s_add_i32 m0, s43, 0xc000
	ds_read_b128 v[166:169], v142
	ds_read_b128 v[170:173], v142 offset:1024
	ds_read_b128 v[204:207], v142 offset:2048
	ds_read_b128 v[208:211], v142 offset:3072
	ds_read_b128 v[212:215], v142 offset:4096
	ds_read_b128 v[216:219], v142 offset:5120
	ds_read_b128 v[220:223], v142 offset:6144
	ds_read_b128 v[224:227], v142 offset:7168
	global_load_lds_dwordx4 v[138:139], off
	v_lshl_add_u64 v[138:139], s[2:3], 0, v[136:137]
	s_add_i32 m0, s43, 0xe000
	s_nop 0
	global_load_lds_dwordx4 v[138:139], off
	s_waitcnt lgkmcnt(8)
	s_barrier
	s_waitcnt lgkmcnt(0)
	s_setprio 1
	s_waitcnt lgkmcnt(0)
	v_mfma_f32_16x16x32_bf16 v[128:131], v[144:147], v[166:169], v[128:131]
	v_mfma_f32_16x16x32_bf16 v[124:127], v[158:161], v[166:169], v[124:127]
	v_mfma_f32_16x16x32_bf16 v[112:115], v[144:147], v[204:207], v[112:115]
	v_mfma_f32_16x16x32_bf16 v[108:111], v[158:161], v[204:207], v[108:111]
	v_mfma_f32_16x16x32_bf16 v[96:99], v[144:147], v[212:215], v[96:99]
	v_mfma_f32_16x16x32_bf16 v[92:95], v[158:161], v[212:215], v[92:95]
	v_mfma_f32_16x16x32_bf16 v[80:83], v[144:147], v[220:223], v[80:83]
	v_mfma_f32_16x16x32_bf16 v[76:79], v[158:161], v[220:223], v[76:79]
	v_mfma_f32_16x16x32_bf16 v[128:131], v[154:157], v[170:173], v[128:131]
	v_mfma_f32_16x16x32_bf16 v[124:127], v[162:165], v[170:173], v[124:127]
	v_mfma_f32_16x16x32_bf16 v[112:115], v[154:157], v[208:211], v[112:115]
	v_mfma_f32_16x16x32_bf16 v[108:111], v[162:165], v[208:211], v[108:111]
	v_mfma_f32_16x16x32_bf16 v[96:99], v[154:157], v[216:219], v[96:99]
	v_mfma_f32_16x16x32_bf16 v[92:95], v[162:165], v[216:219], v[92:95]
	v_mfma_f32_16x16x32_bf16 v[80:83], v[154:157], v[224:227], v[80:83]
	v_mfma_f32_16x16x32_bf16 v[76:79], v[162:165], v[224:227], v[76:79]
	s_setprio 0
	s_barrier
	s_add_i32 s97, 0, 0x14000
	v_add_u32_e32 v138, s97, v140
	s_add_i32 s2, s94, s81
	ds_read_b128 v[228:231], v138
	ds_read_b128 v[232:235], v138 offset:1024
	ds_read_b128 v[236:239], v138 offset:2048
	ds_read_b128 v[240:243], v138 offset:3072
	v_lshl_add_u64 v[138:139], vcc, 0, v[16:17]
	s_mov_b32 m0, s2
	v_lshl_add_u64 v[244:245], vcc, 0, v[132:133]
	global_load_lds_dwordx4 v[138:139], off
	s_add_i32 m0, s2, 0x2000
	s_nop 0
	global_load_lds_dwordx4 v[244:245], off
	s_barrier
	s_waitcnt lgkmcnt(0)
	s_setprio 1
	s_waitcnt lgkmcnt(0)
	v_mfma_f32_16x16x32_bf16 v[120:123], v[228:231], v[166:169], v[120:123]
	v_mfma_f32_16x16x32_bf16 v[116:119], v[236:239], v[166:169], v[116:119]
	v_mfma_f32_16x16x32_bf16 v[104:107], v[228:231], v[204:207], v[104:107]
	v_mfma_f32_16x16x32_bf16 v[100:103], v[236:239], v[204:207], v[100:103]
	v_mfma_f32_16x16x32_bf16 v[88:91], v[228:231], v[212:215], v[88:91]
	v_mfma_f32_16x16x32_bf16 v[84:87], v[236:239], v[212:215], v[84:87]
	v_mfma_f32_16x16x32_bf16 v[72:75], v[228:231], v[220:223], v[72:75]
	v_mfma_f32_16x16x32_bf16 v[68:71], v[236:239], v[220:223], v[68:71]
	v_mfma_f32_16x16x32_bf16 v[120:123], v[232:235], v[170:173], v[120:123]
	v_mfma_f32_16x16x32_bf16 v[116:119], v[240:243], v[170:173], v[116:119]
	v_mfma_f32_16x16x32_bf16 v[104:107], v[232:235], v[208:211], v[104:107]
	v_mfma_f32_16x16x32_bf16 v[100:103], v[240:243], v[208:211], v[100:103]
	v_mfma_f32_16x16x32_bf16 v[88:91], v[232:235], v[216:219], v[88:91]
	v_mfma_f32_16x16x32_bf16 v[84:87], v[240:243], v[216:219], v[84:87]
	v_mfma_f32_16x16x32_bf16 v[72:75], v[232:235], v[224:227], v[72:75]
	v_mfma_f32_16x16x32_bf16 v[68:71], v[240:243], v[224:227], v[68:71]
	s_setprio 0
	s_mov_b32 m0, s43
	v_lshl_add_u64 v[246:247], s[0:1], 0, v[16:17]
	s_barrier
	ds_read_b128 v[166:169], v142 offset:16384
	ds_read_b128 v[170:173], v142 offset:17408
	ds_read_b128 v[204:207], v142 offset:18432
	ds_read_b128 v[208:211], v142 offset:19456
	ds_read_b128 v[212:215], v142 offset:20480
	ds_read_b128 v[216:219], v142 offset:21504
	ds_read_b128 v[220:223], v142 offset:22528
	ds_read_b128 v[224:227], v142 offset:23552
	global_load_lds_dwordx4 v[246:247], off
	v_lshl_add_u64 v[248:249], s[0:1], 0, v[132:133]
	s_mov_b32 m0, s53
	s_nop 0
	global_load_lds_dwordx4 v[248:249], off
	s_barrier
	s_waitcnt lgkmcnt(0)
	s_setprio 1
	s_waitcnt lgkmcnt(0)
	v_mfma_f32_16x16x32_bf16 v[64:67], v[144:147], v[166:169], v[64:67]
	v_mfma_f32_16x16x32_bf16 v[60:63], v[158:161], v[166:169], v[60:63]
	v_mfma_f32_16x16x32_bf16 v[48:51], v[144:147], v[204:207], v[48:51]
	v_mfma_f32_16x16x32_bf16 v[44:47], v[158:161], v[204:207], v[44:47]
	v_mfma_f32_16x16x32_bf16 v[32:35], v[144:147], v[212:215], v[32:35]
	v_mfma_f32_16x16x32_bf16 v[28:31], v[158:161], v[212:215], v[28:31]
	v_mfma_f32_16x16x32_bf16 v[12:15], v[144:147], v[220:223], v[12:15]
	v_mfma_f32_16x16x32_bf16 v[8:11], v[158:161], v[220:223], v[8:11]
	v_mfma_f32_16x16x32_bf16 v[64:67], v[154:157], v[170:173], v[64:67]
	v_mfma_f32_16x16x32_bf16 v[60:63], v[162:165], v[170:173], v[60:63]
	v_mfma_f32_16x16x32_bf16 v[48:51], v[154:157], v[208:211], v[48:51]
	v_mfma_f32_16x16x32_bf16 v[44:47], v[162:165], v[208:211], v[44:47]
	v_mfma_f32_16x16x32_bf16 v[32:35], v[154:157], v[216:219], v[32:35]
	v_mfma_f32_16x16x32_bf16 v[28:31], v[162:165], v[216:219], v[28:31]
	v_mfma_f32_16x16x32_bf16 v[12:15], v[154:157], v[224:227], v[12:15]
	v_mfma_f32_16x16x32_bf16 v[8:11], v[162:165], v[224:227], v[8:11]
	s_setprio 0
	s_barrier
; #define PG8_STAGE(bufoff, gbase, voff) do { _Pragma("unroll") for (int _i = 0; _i < 2; ++_i) \
;         __builtin_amdgcn_global_load_lds((const unsigned*)((const char*)(gbase) + (voff)[_i]), (LAS unsigned*)(lds + (bufoff) + ldsw + _i * 8192), 16, 0, 0); } while (0)
; #define PG8_LDA(dst, b, h) do { _Pragma("unroll") for (int m = 0; m < 4; ++m) _Pragma("unroll") for (int k = 0; k < 2; ++k) dst[m][k] = *(const LAS bf16x8*)(lds + PG8_SA(b, h) + aoff + m * 2048 + k * 1024); } while (0)
; #define PG8_LDB(dst, b, h) do { _Pragma("unroll") for (int n = 0; n < 2; ++n) _Pragma("unroll") for (int k = 0; k < 2; ++k) dst[n][k] = *(const LAS bf16x8*)(lds + PG8_SB(b, h) + boff + n * 2048 + k * 1024); } while (0)
; #define PG8_BAR __builtin_amdgcn_s_barrier()
; template <class Epi>
; __device__ __forceinline__ void gemm_phase(const int tid, LAS unsigned char* lds, const Gemm g, const StaticOrder& S, const Epi& E) {
;     ...
;     for (int t = 0; t < nt; t += 2) {
;       const bool last = (t == nt - 2);
;       const char* a1 = cA + (size_t)(t + 1) * kstep;
;       const char* a2 = last ? nA : cA + (size_t)(t + 2) * kstep; const char* b2 = last ? nB : cB + (size_t)(t + 2) * kstep;
;       const char* a3 = a2 + kstep; const char* b3 = b2 + kstep;
;       PG8_LDB(B0, 0, 0); PG8_SCHED; PG8_LDA(At, 0, 0); PG8_STAGE(PG8_SA(1, 1), a1 + hstep, voffA);
;       PG8_WAIT_L(8); PG8_BAR; PG8_WAIT_L(0); PG8_MMA(0, 0, At, B0); PG8_BAR; PG8_SCHED;
;       PG8_LDB(B1, 0, 1); PG8_STAGE(PG8_SB(0, 0), b2, voffA);
;       PG8_BAR; PG8_WAIT_L(0); PG8_MMA(0, 1, At, B1); PG8_BAR;
;       PG8_LDA(At, 0, 1); PG8_STAGE(PG8_SA(0, 0), a2, voffA);
;       PG8_BAR; PG8_WAIT_L(0); PG8_MMA(1, 0, At, B0); PG8_BAR; PG8_SCHED;
;       PG8_STAGE(PG8_SB(0, 1), b2 + hstep, voffA);
;       PG8_WAIT_V(6); PG8_BAR; PG8_MMA(1, 1, At, B1); PG8_BAR;
;       PG8_LDB(B0, 1, 0); PG8_SCHED; PG8_LDA(At, 1, 0); PG8_STAGE(PG8_SA(0, 1), a2 + hstep, voffA);
;       PG8_WAIT_L(8); PG8_BAR; PG8_WAIT_L(0); PG8_MMA(0, 0, At, B0); PG8_BAR; PG8_SCHED;
;       PG8_LDB(B1, 1, 1); PG8_STAGE(PG8_SB(1, 0), b3, voffA);
;       PG8_BAR; PG8_WAIT_L(0); PG8_MMA(0, 1, At, B1); PG8_BAR;
;       PG8_LDA(At, 1, 1); PG8_STAGE(PG8_SA(1, 0), a3, voffA);
;       PG8_BAR; PG8_WAIT_L(0); PG8_MMA(1, 0, At, B0); PG8_BAR; PG8_SCHED;
;       PG8_STAGE(PG8_SB(1, 1), b3 + hstep, voffA);
;       PG8_WAIT_V(6); PG8_BAR; PG8_MMA(1, 1, At, B1); PG8_BAR;
	s_add_u32 s2, vcc_lo, 0x80000
	s_addc_u32 s3, vcc_hi, 0
	s_add_i32 s94, s97, s81
	v_lshl_add_u64 v[144:145], s[2:3], 0, v[16:17]
	s_mov_b32 m0, s94
	s_nop 0
	global_load_lds_dwordx4 v[144:145], off
	v_lshl_add_u64 v[144:145], s[2:3], 0, v[132:133]
	s_add_i32 m0, s94, 0x2000
	s_nop 0
	global_load_lds_dwordx4 v[144:145], off
	s_waitcnt vmcnt(6)
	s_barrier
	s_setprio 1
	v_mfma_f32_16x16x32_bf16 v[56:59], v[228:231], v[166:169], v[56:59]
	v_mfma_f32_16x16x32_bf16 v[52:55], v[236:239], v[166:169], v[52:55]
	v_mfma_f32_16x16x32_bf16 v[40:43], v[228:231], v[204:207], v[40:43]
	v_mfma_f32_16x16x32_bf16 v[36:39], v[236:239], v[204:207], v[36:39]
	v_mfma_f32_16x16x32_bf16 v[24:27], v[228:231], v[212:215], v[24:27]
	v_mfma_f32_16x16x32_bf16 v[20:23], v[236:239], v[212:215], v[20:23]
	v_mfma_f32_16x16x32_bf16 v[4:7], v[228:231], v[220:223], v[4:7]
	v_mfma_f32_16x16x32_bf16 v[0:3], v[236:239], v[220:223], v[0:3]
	v_mfma_f32_16x16x32_bf16 v[56:59], v[232:235], v[170:173], v[56:59]
	v_mfma_f32_16x16x32_bf16 v[52:55], v[240:243], v[170:173], v[52:55]
	v_mfma_f32_16x16x32_bf16 v[40:43], v[232:235], v[208:211], v[40:43]
	v_mfma_f32_16x16x32_bf16 v[36:39], v[240:243], v[208:211], v[36:39]
	v_mfma_f32_16x16x32_bf16 v[24:27], v[232:235], v[216:219], v[24:27]
	v_mfma_f32_16x16x32_bf16 v[20:23], v[240:243], v[216:219], v[20:23]
	v_mfma_f32_16x16x32_bf16 v[4:7], v[232:235], v[224:227], v[4:7]
	v_mfma_f32_16x16x32_bf16 v[0:3], v[240:243], v[224:227], v[0:3]
	s_setprio 0
	s_add_i32 s2, 0, 0x18000
	v_add_u32_e32 v143, s2, v140
	s_barrier
	ds_read_b128 v[144:147], v143
	ds_read_b128 v[154:157], v143 offset:1024
	ds_read_b128 v[158:161], v143 offset:2048
	ds_read_b128 v[162:165], v143 offset:3072
	s_add_u32 s0, s0, 0x80000
	s_addc_u32 s1, s1, 0
	s_mov_b32 m0, s82
	v_lshl_add_u64 v[228:229], s[0:1], 0, v[16:17]
	ds_read_b128 v[166:169], v142 offset:32768
	ds_read_b128 v[170:173], v142 offset:33792
	ds_read_b128 v[204:207], v142 offset:34816
	ds_read_b128 v[208:211], v142 offset:35840
	ds_read_b128 v[212:215], v142 offset:36864
	ds_read_b128 v[216:219], v142 offset:37888
	ds_read_b128 v[220:223], v142 offset:38912
	ds_read_b128 v[224:227], v142 offset:39936
	global_load_lds_dwordx4 v[228:229], off
	v_lshl_add_u64 v[228:229], s[0:1], 0, v[132:133]
	s_mov_b32 m0, s83
	s_nop 0
	global_load_lds_dwordx4 v[228:229], off
	s_waitcnt lgkmcnt(8)
	s_barrier
	s_waitcnt lgkmcnt(0)
	s_setprio 1
	s_waitcnt lgkmcnt(0)
	v_mfma_f32_16x16x32_bf16 v[128:131], v[144:147], v[166:169], v[128:131]
	v_mfma_f32_16x16x32_bf16 v[124:127], v[158:161], v[166:169], v[124:127]
	v_mfma_f32_16x16x32_bf16 v[112:115], v[144:147], v[204:207], v[112:115]
	v_mfma_f32_16x16x32_bf16 v[108:111], v[158:161], v[204:207], v[108:111]
	v_mfma_f32_16x16x32_bf16 v[96:99], v[144:147], v[212:215], v[96:99]
	v_mfma_f32_16x16x32_bf16 v[92:95], v[158:161], v[212:215], v[92:95]
	v_mfma_f32_16x16x32_bf16 v[80:83], v[144:147], v[220:223], v[80:83]
	v_mfma_f32_16x16x32_bf16 v[76:79], v[158:161], v[220:223], v[76:79]
	v_mfma_f32_16x16x32_bf16 v[128:131], v[154:157], v[170:173], v[128:131]
	v_mfma_f32_16x16x32_bf16 v[124:127], v[162:165], v[170:173], v[124:127]
	v_mfma_f32_16x16x32_bf16 v[112:115], v[154:157], v[208:211], v[112:115]
	v_mfma_f32_16x16x32_bf16 v[108:111], v[162:165], v[208:211], v[108:111]
	v_mfma_f32_16x16x32_bf16 v[96:99], v[154:157], v[216:219], v[96:99]
	v_mfma_f32_16x16x32_bf16 v[92:95], v[162:165], v[216:219], v[92:95]
	v_mfma_f32_16x16x32_bf16 v[80:83], v[154:157], v[224:227], v[80:83]
	v_mfma_f32_16x16x32_bf16 v[76:79], v[162:165], v[224:227], v[76:79]
	s_setprio 0
	s_barrier
	s_add_i32 s3, 0, 0x1c000
	s_add_i32 s0, s2, s81
	v_add_u32_e32 v143, s3, v140
	v_lshl_add_u64 v[138:139], v[138:139], 0, s[4:5]
	s_mov_b32 m0, s0
	ds_read_b128 v[228:231], v143
	ds_read_b128 v[232:235], v143 offset:1024
	ds_read_b128 v[236:239], v143 offset:2048
	ds_read_b128 v[240:243], v143 offset:3072
	global_load_lds_dwordx4 v[138:139], off
	v_lshl_add_u64 v[138:139], v[244:245], 0, s[4:5]
	s_add_i32 m0, s0, 0x2000
	s_nop 0
	global_load_lds_dwordx4 v[138:139], off
	s_barrier
	s_waitcnt lgkmcnt(0)
	s_setprio 1
	s_waitcnt lgkmcnt(0)
	v_mfma_f32_16x16x32_bf16 v[120:123], v[228:231], v[166:169], v[120:123]
	v_mfma_f32_16x16x32_bf16 v[116:119], v[236:239], v[166:169], v[116:119]
	v_mfma_f32_16x16x32_bf16 v[104:107], v[228:231], v[204:207], v[104:107]
	v_mfma_f32_16x16x32_bf16 v[100:103], v[236:239], v[204:207], v[100:103]
	v_mfma_f32_16x16x32_bf16 v[88:91], v[228:231], v[212:215], v[88:91]
	v_mfma_f32_16x16x32_bf16 v[84:87], v[236:239], v[212:215], v[84:87]
	v_mfma_f32_16x16x32_bf16 v[72:75], v[228:231], v[220:223], v[72:75]
	v_mfma_f32_16x16x32_bf16 v[68:71], v[236:239], v[220:223], v[68:71]
	v_mfma_f32_16x16x32_bf16 v[120:123], v[232:235], v[170:173], v[120:123]
	v_mfma_f32_16x16x32_bf16 v[116:119], v[240:243], v[170:173], v[116:119]
	v_mfma_f32_16x16x32_bf16 v[104:107], v[232:235], v[208:211], v[104:107]
	v_mfma_f32_16x16x32_bf16 v[100:103], v[240:243], v[208:211], v[100:103]
	v_mfma_f32_16x16x32_bf16 v[88:91], v[232:235], v[216:219], v[88:91]
	v_mfma_f32_16x16x32_bf16 v[84:87], v[240:243], v[216:219], v[84:87]
	v_mfma_f32_16x16x32_bf16 v[72:75], v[232:235], v[224:227], v[72:75]
	v_mfma_f32_16x16x32_bf16 v[68:71], v[240:243], v[224:227], v[68:71]
	s_setprio 0
	s_mov_b32 m0, s85
	v_lshl_add_u64 v[138:139], v[246:247], 0, s[4:5]
	s_barrier
	ds_read_b128 v[166:169], v142 offset:49152
	ds_read_b128 v[170:173], v142 offset:50176
	ds_read_b128 v[204:207], v142 offset:51200
	ds_read_b128 v[208:211], v142 offset:52224
	ds_read_b128 v[212:215], v142 offset:53248
	ds_read_b128 v[216:219], v142 offset:54272
	ds_read_b128 v[220:223], v142 offset:55296
	ds_read_b128 v[224:227], v142 offset:56320
	global_load_lds_dwordx4 v[138:139], off
	v_lshl_add_u64 v[138:139], v[248:249], 0, s[4:5]
	s_mov_b32 m0, s86
	s_nop 0
	global_load_lds_dwordx4 v[138:139], off
	s_barrier
; __device__ __forceinline__ float siluf_(float x) { return x * sigmoidf_(x); }
; #define PG8_STAGE(bufoff, gbase, voff) do { _Pragma("unroll") for (int _i = 0; _i < 2; ++_i) \
;         __builtin_amdgcn_global_load_lds((const unsigned*)((const char*)(gbase) + (voff)[_i]), (LAS unsigned*)(lds + (bufoff) + ldsw + _i * 8192), 16, 0, 0); } while (0)
; #define PG8_LDA(dst, b, h) do { _Pragma("unroll") for (int m = 0; m < 4; ++m) _Pragma("unroll") for (int k = 0; k < 2; ++k) dst[m][k] = *(const LAS bf16x8*)(lds + PG8_SA(b, h) + aoff + m * 2048 + k * 1024); } while (0)
; #define PG8_LDB(dst, b, h) do { _Pragma("unroll") for (int n = 0; n < 2; ++n) _Pragma("unroll") for (int k = 0; k < 2; ++k) dst[n][k] = *(const LAS bf16x8*)(lds + PG8_SB(b, h) + boff + n * 2048 + k * 1024); } while (0)
;   __device__ __forceinline__ void operator()(const f32x4 (&acc)[2][2][4][2], const Unit& u, int wr, int wc, int fr, int fq) const {
;     const int row0 = u.pm * BM + wr * 64 + fr;
; #pragma unroll
;     for (int ai = 0; ai < 2; ++ai)
; #pragma unroll
;       for (int m = 0; m < 4; ++m) {
;         bfu* rowp = act + (size_t)(row0 + ai * HALF + m * 16) * DFF;
; #pragma unroll
;         for (int bj = 0; bj < 2; ++bj) {
;           const int oc = (u.pn * BM + bj * HALF + wc * 32) / 2 + 4 * fq;
;           const f32x4 g = acc[ai][bj][m][0], up = acc[ai][bj][m][1];
;           uint2 o;
;           o.x = pack2(siluf_(g[0]) * up[0], siluf_(g[1]) * up[1]);
;           o.y = pack2(siluf_(g[2]) * up[2], siluf_(g[3]) * up[3]);
;           *reinterpret_cast<uint2*>(rowp + oc) = o;
;         }
;       }
;   }
; template <class Epi>
; __device__ __forceinline__ void gemm_phase(const int tid, LAS unsigned char* lds, const Gemm g, const StaticOrder& S, const Epi& E) {
;     ...
;       PG8_WAIT_V(6); PG8_BAR; PG8_MMA(1, 1, At, B1); PG8_BAR;
;       PG8_LDB(B0, 1, 0); PG8_SCHED; PG8_LDA(At, 1, 0); PG8_STAGE(PG8_SA(0, 1), a2 + hstep, voffA);
;       PG8_WAIT_L(8); PG8_BAR; PG8_WAIT_L(0); PG8_MMA(0, 0, At, B0); PG8_BAR; PG8_SCHED;
;       PG8_LDB(B1, 1, 1); PG8_STAGE(PG8_SB(1, 0), b3, voffA);
;       PG8_BAR; PG8_WAIT_L(0); PG8_MMA(0, 1, At, B1); PG8_BAR;
;       PG8_LDA(At, 1, 1); PG8_STAGE(PG8_SA(1, 0), a3, voffA);
;       PG8_BAR; PG8_WAIT_L(0); PG8_MMA(1, 0, At, B0); PG8_BAR; PG8_SCHED;
;       PG8_STAGE(PG8_SB(1, 1), b3 + hstep, voffA);
;       PG8_WAIT_V(6); PG8_BAR; PG8_MMA(1, 1, At, B1); PG8_BAR;
	s_waitcnt lgkmcnt(0)
	s_setprio 1
	s_waitcnt lgkmcnt(0)
	v_mfma_f32_16x16x32_bf16 v[64:67], v[144:147], v[166:169], v[64:67]
	v_mfma_f32_16x16x32_bf16 v[60:63], v[158:161], v[166:169], v[60:63]
	v_mfma_f32_16x16x32_bf16 v[48:51], v[144:147], v[204:207], v[48:51]
	v_mfma_f32_16x16x32_bf16 v[44:47], v[158:161], v[204:207], v[44:47]
	v_mfma_f32_16x16x32_bf16 v[32:35], v[144:147], v[212:215], v[32:35]
	v_mfma_f32_16x16x32_bf16 v[28:31], v[158:161], v[212:215], v[28:31]
	v_mfma_f32_16x16x32_bf16 v[12:15], v[144:147], v[220:223], v[12:15]
	v_mfma_f32_16x16x32_bf16 v[8:11], v[158:161], v[220:223], v[8:11]
	v_mfma_f32_16x16x32_bf16 v[64:67], v[154:157], v[170:173], v[64:67]
	v_mfma_f32_16x16x32_bf16 v[60:63], v[162:165], v[170:173], v[60:63]
	v_mfma_f32_16x16x32_bf16 v[48:51], v[154:157], v[208:211], v[48:51]
	v_mfma_f32_16x16x32_bf16 v[44:47], v[162:165], v[208:211], v[44:47]
	v_mfma_f32_16x16x32_bf16 v[32:35], v[154:157], v[216:219], v[32:35]
	v_mfma_f32_16x16x32_bf16 v[28:31], v[162:165], v[216:219], v[28:31]
	v_mfma_f32_16x16x32_bf16 v[12:15], v[154:157], v[224:227], v[12:15]
	v_mfma_f32_16x16x32_bf16 v[8:11], v[162:165], v[224:227], v[8:11]
	s_setprio 0
	s_barrier
	s_add_u32 s0, vcc_lo, 0x80080
	s_addc_u32 s1, vcc_hi, 0
	s_add_i32 s2, s3, s81
	v_lshl_add_u64 v[138:139], s[0:1], 0, v[16:17]
	s_mov_b32 m0, s2
	s_nop 0
	global_load_lds_dwordx4 v[138:139], off
	v_lshl_add_u64 v[138:139], s[0:1], 0, v[132:133]
	s_add_i32 m0, s2, 0x2000
	s_nop 0
	global_load_lds_dwordx4 v[138:139], off
	s_waitcnt vmcnt(6)
	s_barrier
	s_setprio 1
	v_mfma_f32_16x16x32_bf16 v[56:59], v[228:231], v[166:169], v[56:59]
	v_mfma_f32_16x16x32_bf16 v[52:55], v[236:239], v[166:169], v[52:55]
	v_mfma_f32_16x16x32_bf16 v[40:43], v[228:231], v[204:207], v[40:43]
	v_mfma_f32_16x16x32_bf16 v[36:39], v[236:239], v[204:207], v[36:39]
	v_mfma_f32_16x16x32_bf16 v[24:27], v[228:231], v[212:215], v[24:27]
	v_mfma_f32_16x16x32_bf16 v[20:23], v[236:239], v[212:215], v[20:23]
	v_mfma_f32_16x16x32_bf16 v[4:7], v[228:231], v[220:223], v[4:7]
	v_mfma_f32_16x16x32_bf16 v[0:3], v[236:239], v[220:223], v[0:3]
	v_mfma_f32_16x16x32_bf16 v[56:59], v[232:235], v[170:173], v[56:59]
	v_mfma_f32_16x16x32_bf16 v[52:55], v[240:243], v[170:173], v[52:55]
	v_mfma_f32_16x16x32_bf16 v[40:43], v[232:235], v[208:211], v[40:43]
	v_mfma_f32_16x16x32_bf16 v[36:39], v[240:243], v[208:211], v[36:39]
	v_mfma_f32_16x16x32_bf16 v[24:27], v[232:235], v[216:219], v[24:27]
	v_mfma_f32_16x16x32_bf16 v[20:23], v[240:243], v[216:219], v[20:23]
	v_mfma_f32_16x16x32_bf16 v[4:7], v[232:235], v[224:227], v[4:7]
	v_mfma_f32_16x16x32_bf16 v[0:3], v[240:243], v[224:227], v[0:3]
	s_setprio 0
	s_add_i32 s13, s13, 2
	s_add_u32 s45, s45, 0x100
	s_addc_u32 s12, s12, 0
	s_cmp_gt_u32 s13, 29
	s_mov_b64 s[2:3], s[30:31]
	s_barrier
	s_cbranch_scc0 .LBB0_847
	v_mul_f32_e32 v145, 0xbfb8aa3b, v128
	v_exp_f32_e32 v145, v145
	s_lshl_b32 s0, s42, 8
	s_or_b32 s0, s0, s84
	s_ashr_i32 s0, s0, 1
	v_add_f32_e32 v145, 1.0, v145
	v_rcp_f32_e32 v154, v145
	v_mul_f32_e32 v145, 0xbfb8aa3b, v129
	v_exp_f32_e32 v145, v145
	v_or_b32_e32 v144, s0, v141
	v_lshl_add_u32 v143, s52, 8, v19
	v_mov_b64_e32 v[138:139], s[22:23]
	v_add_f32_e32 v145, 1.0, v145
	v_rcp_f32_e32 v155, v145
	s_movk_i32 s2, 0x2b00
	v_ashrrev_i32_e32 v145, 31, v144
	v_mad_i64_i32 v[146:147], s[0:1], v143, s2, v[138:139]
	v_pk_mul_f32 v[128:129], v[128:129], v[154:155]
	s_and_b64 vcc, exec, s[40:41]
	v_pk_mul_f32 v[124:125], v[124:125], v[128:129]
	s_mov_b32 s42, s28
	v_cvt_pk_bf16_f32 v128, v124, v125
	v_mul_f32_e32 v124, 0xbfb8aa3b, v130
	v_mul_f32_e32 v125, 0xbfb8aa3b, v131
	v_exp_f32_e32 v124, v124
	v_exp_f32_e32 v125, v125
	s_mov_b32 s52, s44
	s_mov_b64 s[30:31], s[48:49]
	v_add_f32_e32 v124, 1.0, v124
	v_add_f32_e32 v125, 1.0, v125
	v_rcp_f32_e32 v124, v124
	v_rcp_f32_e32 v125, v125
	s_mov_b32 s48, 0x38e38e39
	v_pk_mul_f32 v[124:125], v[130:131], v[124:125]
	s_nop 0
	v_pk_mul_f32 v[124:125], v[126:127], v[124:125]
	s_nop 0
	v_cvt_pk_bf16_f32 v129, v124, v125
	v_lshlrev_b64 v[124:125], 1, v[144:145]
	v_and_b32_e32 v250, 4, v141
	v_mul_u32_u24_e32 v250, 30, v250
	v_mov_b32_e32 v251, 0
	v_lshl_add_u64 v[124:125], v[124:125], 0, v[250:251]
	v_lshl_add_u64 v[126:127], v[146:147], 0, v[124:125]
	v_mov_b32_e32 v148, v128
	v_mov_b32_e32 v149, v129
	v_mul_f32_e32 v128, 0xbfb8aa3b, v120
	v_mul_f32_e32 v129, 0xbfb8aa3b, v121
	v_exp_f32_e32 v128, v128
	v_exp_f32_e32 v129, v129
	v_add_f32_e32 v128, 1.0, v128
	v_add_f32_e32 v129, 1.0, v129
	v_rcp_f32_e32 v128, v128
	v_rcp_f32_e32 v129, v129
	s_nop 0
	v_pk_mul_f32 v[120:121], v[120:121], v[128:129]
	s_nop 0
	v_pk_mul_f32 v[116:117], v[116:117], v[120:121]
	s_nop 0
	v_cvt_pk_bf16_f32 v116, v116, v117
	v_mul_f32_e32 v117, 0xbfb8aa3b, v122
	v_exp_f32_e32 v117, v117
	s_nop 0
	v_add_f32_e32 v117, 1.0, v117
	v_rcp_f32_e32 v120, v117
	v_mul_f32_e32 v117, 0xbfb8aa3b, v123
	v_exp_f32_e32 v117, v117
	s_nop 0
	v_add_f32_e32 v117, 1.0, v117
	v_rcp_f32_e32 v121, v117
	s_nop 0
	v_pk_mul_f32 v[120:121], v[122:123], v[120:121]
	s_nop 0
	v_pk_mul_f32 v[118:119], v[118:119], v[120:121]
	s_nop 0
	v_cvt_pk_bf16_f32 v117, v118, v119
	v_mul_f32_e32 v118, 0xbfb8aa3b, v112
	v_mul_f32_e32 v119, 0xbfb8aa3b, v113
	v_exp_f32_e32 v118, v118
	v_exp_f32_e32 v119, v119
	v_mov_b32_e32 v150, v116
	v_mov_b32_e32 v151, v117
	s_nop 1
	v_permlane16_swap_b32_e32 v148, v150
	v_permlane16_swap_b32_e32 v149, v151
	global_store_dwordx4 v[126:127], v[148:151], off
	v_or_b32_e32 v116, 16, v143
	v_add_f32_e32 v118, 1.0, v118
	v_add_f32_e32 v119, 1.0, v119
	v_rcp_f32_e32 v118, v118
	v_rcp_f32_e32 v119, v119
	v_mad_i64_i32 v[116:117], s[0:1], v116, s2, v[138:139]
	v_pk_mul_f32 v[112:113], v[112:113], v[118:119]
; __device__ __forceinline__ float siluf_(float x) { return x * sigmoidf_(x); }
;   __device__ __forceinline__ void operator()(const f32x4 (&acc)[2][2][4][2], const Unit& u, int wr, int wc, int fr, int fq) const {
;     const int row0 = u.pm * BM + wr * 64 + fr;
; #pragma unroll
;     for (int ai = 0; ai < 2; ++ai)
; #pragma unroll
;       for (int m = 0; m < 4; ++m) {
;         bfu* rowp = act + (size_t)(row0 + ai * HALF + m * 16) * DFF;
; #pragma unroll
;         for (int bj = 0; bj < 2; ++bj) {
;           const int oc = (u.pn * BM + bj * HALF + wc * 32) / 2 + 4 * fq;
;           const f32x4 g = acc[ai][bj][m][0], up = acc[ai][bj][m][1];
;           uint2 o;
;           o.x = pack2(siluf_(g[0]) * up[0], siluf_(g[1]) * up[1]);
;           o.y = pack2(siluf_(g[2]) * up[2], siluf_(g[3]) * up[3]);
;           *reinterpret_cast<uint2*>(rowp + oc) = o;
;         }
;       }
;   }
	s_nop 0
	v_pk_mul_f32 v[108:109], v[108:109], v[112:113]
	s_nop 0
	v_cvt_pk_bf16_f32 v108, v108, v109
	v_mul_f32_e32 v109, 0xbfb8aa3b, v114
	v_exp_f32_e32 v109, v109
	s_nop 0
	v_add_f32_e32 v109, 1.0, v109
	v_rcp_f32_e32 v112, v109
	v_mul_f32_e32 v109, 0xbfb8aa3b, v115
	v_exp_f32_e32 v109, v109
	s_nop 0
	v_add_f32_e32 v109, 1.0, v109
	v_rcp_f32_e32 v113, v109
	s_nop 0
	v_pk_mul_f32 v[112:113], v[114:115], v[112:113]
	s_nop 0
	v_pk_mul_f32 v[110:111], v[110:111], v[112:113]
	s_nop 0
	v_cvt_pk_bf16_f32 v109, v110, v111
	v_lshl_add_u64 v[110:111], v[116:117], 0, v[124:125]
	v_mov_b32_e32 v148, v108
	v_mov_b32_e32 v149, v109
	v_mul_f32_e32 v108, 0xbfb8aa3b, v104
	v_mul_f32_e32 v109, 0xbfb8aa3b, v105
	v_exp_f32_e32 v108, v108
	v_exp_f32_e32 v109, v109
	v_add_f32_e32 v108, 1.0, v108
	v_add_f32_e32 v109, 1.0, v109
	v_rcp_f32_e32 v108, v108
	v_rcp_f32_e32 v109, v109
	s_nop 0
	v_pk_mul_f32 v[104:105], v[104:105], v[108:109]
	s_nop 0
	v_pk_mul_f32 v[100:101], v[100:101], v[104:105]
	s_nop 0
	v_cvt_pk_bf16_f32 v100, v100, v101
	v_mul_f32_e32 v101, 0xbfb8aa3b, v106
	v_exp_f32_e32 v101, v101
	s_nop 0
	v_add_f32_e32 v101, 1.0, v101
	v_rcp_f32_e32 v104, v101
	v_mul_f32_e32 v101, 0xbfb8aa3b, v107
	v_exp_f32_e32 v101, v101
	s_nop 0
	v_add_f32_e32 v101, 1.0, v101
	v_rcp_f32_e32 v105, v101
	s_nop 0
	v_pk_mul_f32 v[104:105], v[106:107], v[104:105]
	s_nop 0
	v_pk_mul_f32 v[102:103], v[102:103], v[104:105]
	s_nop 0
	v_cvt_pk_bf16_f32 v101, v102, v103
	v_mul_f32_e32 v102, 0xbfb8aa3b, v96
	v_mul_f32_e32 v103, 0xbfb8aa3b, v97
	v_exp_f32_e32 v102, v102
	v_exp_f32_e32 v103, v103
	v_mov_b32_e32 v150, v100
	v_mov_b32_e32 v151, v101
	s_nop 1
	v_permlane16_swap_b32_e32 v148, v150
	v_permlane16_swap_b32_e32 v149, v151
	global_store_dwordx4 v[110:111], v[148:151], off
	v_or_b32_e32 v100, 32, v143
	v_add_f32_e32 v102, 1.0, v102
	v_add_f32_e32 v103, 1.0, v103
	v_rcp_f32_e32 v102, v102
	v_rcp_f32_e32 v103, v103
	v_mad_i64_i32 v[100:101], s[0:1], v100, s2, v[138:139]
	v_pk_mul_f32 v[96:97], v[96:97], v[102:103]
	s_nop 0
	v_pk_mul_f32 v[92:93], v[92:93], v[96:97]
	s_nop 0
	v_cvt_pk_bf16_f32 v92, v92, v93
	v_mul_f32_e32 v93, 0xbfb8aa3b, v98
	v_exp_f32_e32 v93, v93
	s_nop 0
	v_add_f32_e32 v93, 1.0, v93
	v_rcp_f32_e32 v96, v93
	v_mul_f32_e32 v93, 0xbfb8aa3b, v99
	v_exp_f32_e32 v93, v93
	s_nop 0
	v_add_f32_e32 v93, 1.0, v93
	v_rcp_f32_e32 v97, v93
	s_nop 0
	v_pk_mul_f32 v[96:97], v[98:99], v[96:97]
	s_nop 0
	v_pk_mul_f32 v[94:95], v[94:95], v[96:97]
	s_nop 0
	v_cvt_pk_bf16_f32 v93, v94, v95
	v_lshl_add_u64 v[94:95], v[100:101], 0, v[124:125]
	v_mov_b32_e32 v148, v92
	v_mov_b32_e32 v149, v93
	v_mul_f32_e32 v92, 0xbfb8aa3b, v88
	v_mul_f32_e32 v93, 0xbfb8aa3b, v89
	v_exp_f32_e32 v92, v92
	v_exp_f32_e32 v93, v93
	v_add_f32_e32 v92, 1.0, v92
	v_add_f32_e32 v93, 1.0, v93
	v_rcp_f32_e32 v92, v92
	v_rcp_f32_e32 v93, v93
	s_nop 0
	v_pk_mul_f32 v[88:89], v[88:89], v[92:93]
	s_nop 0
	v_pk_mul_f32 v[84:85], v[84:85], v[88:89]
	s_nop 0
	v_cvt_pk_bf16_f32 v84, v84, v85
	v_mul_f32_e32 v85, 0xbfb8aa3b, v90
	v_exp_f32_e32 v85, v85
	s_nop 0
	v_add_f32_e32 v85, 1.0, v85
	v_rcp_f32_e32 v88, v85
	v_mul_f32_e32 v85, 0xbfb8aa3b, v91
	v_exp_f32_e32 v85, v85
	s_nop 0
	v_add_f32_e32 v85, 1.0, v85
	v_rcp_f32_e32 v89, v85
	s_nop 0
	v_pk_mul_f32 v[88:89], v[90:91], v[88:89]
	s_nop 0
	v_pk_mul_f32 v[86:87], v[86:87], v[88:89]
	s_nop 0
	v_cvt_pk_bf16_f32 v85, v86, v87
	v_mul_f32_e32 v86, 0xbfb8aa3b, v80
	v_mul_f32_e32 v87, 0xbfb8aa3b, v81
	v_exp_f32_e32 v86, v86
	v_exp_f32_e32 v87, v87
	v_mov_b32_e32 v150, v84
	v_mov_b32_e32 v151, v85
	s_nop 1
	v_permlane16_swap_b32_e32 v148, v150
	v_permlane16_swap_b32_e32 v149, v151
	global_store_dwordx4 v[94:95], v[148:151], off
	v_or_b32_e32 v84, 48, v143
	v_add_f32_e32 v86, 1.0, v86
	v_add_f32_e32 v87, 1.0, v87
	v_rcp_f32_e32 v86, v86
	v_rcp_f32_e32 v87, v87
	v_mad_i64_i32 v[84:85], s[0:1], v84, s2, v[138:139]
	v_pk_mul_f32 v[80:81], v[80:81], v[86:87]
	s_nop 0
	v_pk_mul_f32 v[76:77], v[76:77], v[80:81]
	s_nop 0
	v_cvt_pk_bf16_f32 v76, v76, v77
	v_mul_f32_e32 v77, 0xbfb8aa3b, v82
	v_exp_f32_e32 v77, v77
	s_nop 0
	v_add_f32_e32 v77, 1.0, v77
	v_rcp_f32_e32 v80, v77
	v_mul_f32_e32 v77, 0xbfb8aa3b, v83
	v_exp_f32_e32 v77, v77
	s_nop 0
	v_add_f32_e32 v77, 1.0, v77
	v_rcp_f32_e32 v81, v77
	s_nop 0
	v_pk_mul_f32 v[80:81], v[82:83], v[80:81]
	s_nop 0
	v_pk_mul_f32 v[78:79], v[78:79], v[80:81]
	s_nop 0
	v_cvt_pk_bf16_f32 v77, v78, v79
	v_lshl_add_u64 v[78:79], v[84:85], 0, v[124:125]
	v_mov_b32_e32 v148, v76
	v_mov_b32_e32 v149, v77
	v_mul_f32_e32 v76, 0xbfb8aa3b, v72
	v_mul_f32_e32 v77, 0xbfb8aa3b, v73
	v_exp_f32_e32 v76, v76
	v_exp_f32_e32 v77, v77
	v_add_f32_e32 v76, 1.0, v76
	v_add_f32_e32 v77, 1.0, v77
	v_rcp_f32_e32 v76, v76
	v_rcp_f32_e32 v77, v77
	s_nop 0
	v_pk_mul_f32 v[72:73], v[72:73], v[76:77]
	s_nop 0
	v_pk_mul_f32 v[68:69], v[68:69], v[72:73]
	s_nop 0
	v_cvt_pk_bf16_f32 v68, v68, v69
	v_mul_f32_e32 v69, 0xbfb8aa3b, v74
	v_exp_f32_e32 v69, v69
	s_nop 0
	v_add_f32_e32 v69, 1.0, v69
	v_rcp_f32_e32 v72, v69
	v_mul_f32_e32 v69, 0xbfb8aa3b, v75
	v_exp_f32_e32 v69, v69
	s_nop 0
	v_add_f32_e32 v69, 1.0, v69
	v_rcp_f32_e32 v73, v69
	s_nop 0
	v_pk_mul_f32 v[72:73], v[74:75], v[72:73]
	s_nop 0
	v_pk_mul_f32 v[70:71], v[70:71], v[72:73]
	s_nop 0
	v_cvt_pk_bf16_f32 v69, v70, v71
	v_mul_f32_e32 v70, 0xbfb8aa3b, v64
	v_mul_f32_e32 v71, 0xbfb8aa3b, v65
	v_exp_f32_e32 v70, v70
	v_exp_f32_e32 v71, v71
	v_mov_b32_e32 v150, v68
	v_mov_b32_e32 v151, v69
	s_nop 1
	v_permlane16_swap_b32_e32 v148, v150
	v_permlane16_swap_b32_e32 v149, v151
	global_store_dwordx4 v[78:79], v[148:151], off
	v_add_u32_e32 v68, 0x80, v143
	v_add_f32_e32 v70, 1.0, v70
	v_add_f32_e32 v71, 1.0, v71
; __device__ __forceinline__ float siluf_(float x) { return x * sigmoidf_(x); }
;   __device__ __forceinline__ void operator()(const f32x4 (&acc)[2][2][4][2], const Unit& u, int wr, int wc, int fr, int fq) const {
;     const int row0 = u.pm * BM + wr * 64 + fr;
; #pragma unroll
;     for (int ai = 0; ai < 2; ++ai)
; #pragma unroll
;       for (int m = 0; m < 4; ++m) {
;         bfu* rowp = act + (size_t)(row0 + ai * HALF + m * 16) * DFF;
; #pragma unroll
;         for (int bj = 0; bj < 2; ++bj) {
;           const int oc = (u.pn * BM + bj * HALF + wc * 32) / 2 + 4 * fq;
;           const f32x4 g = acc[ai][bj][m][0], up = acc[ai][bj][m][1];
;           uint2 o;
;           o.x = pack2(siluf_(g[0]) * up[0], siluf_(g[1]) * up[1]);
;           o.y = pack2(siluf_(g[2]) * up[2], siluf_(g[3]) * up[3]);
;           *reinterpret_cast<uint2*>(rowp + oc) = o;
;         }
;       }
;   }
	v_rcp_f32_e32 v70, v70
	v_rcp_f32_e32 v71, v71
	v_mad_i64_i32 v[68:69], s[0:1], v68, s2, v[138:139]
	v_pk_mul_f32 v[64:65], v[64:65], v[70:71]
	s_nop 0
	v_pk_mul_f32 v[60:61], v[60:61], v[64:65]
	s_nop 0
	v_cvt_pk_bf16_f32 v60, v60, v61
	v_mul_f32_e32 v61, 0xbfb8aa3b, v66
	v_exp_f32_e32 v61, v61
	s_nop 0
	v_add_f32_e32 v61, 1.0, v61
	v_rcp_f32_e32 v64, v61
	v_mul_f32_e32 v61, 0xbfb8aa3b, v67
	v_exp_f32_e32 v61, v61
	s_nop 0
	v_add_f32_e32 v61, 1.0, v61
	v_rcp_f32_e32 v65, v61
	s_nop 0
	v_pk_mul_f32 v[64:65], v[66:67], v[64:65]
	s_nop 0
	v_pk_mul_f32 v[62:63], v[62:63], v[64:65]
	s_nop 0
	v_cvt_pk_bf16_f32 v61, v62, v63
	v_lshl_add_u64 v[62:63], v[68:69], 0, v[124:125]
	v_mov_b32_e32 v148, v60
	v_mov_b32_e32 v149, v61
	v_mul_f32_e32 v60, 0xbfb8aa3b, v56
	v_mul_f32_e32 v61, 0xbfb8aa3b, v57
	v_exp_f32_e32 v60, v60
	v_exp_f32_e32 v61, v61
	v_add_f32_e32 v60, 1.0, v60
	v_add_f32_e32 v61, 1.0, v61
	v_rcp_f32_e32 v60, v60
	v_rcp_f32_e32 v61, v61
	s_nop 0
	v_pk_mul_f32 v[56:57], v[56:57], v[60:61]
	s_nop 0
	v_pk_mul_f32 v[52:53], v[52:53], v[56:57]
	s_nop 0
	v_cvt_pk_bf16_f32 v52, v52, v53
	v_mul_f32_e32 v53, 0xbfb8aa3b, v58
	v_exp_f32_e32 v53, v53
	s_nop 0
	v_add_f32_e32 v53, 1.0, v53
	v_rcp_f32_e32 v56, v53
	v_mul_f32_e32 v53, 0xbfb8aa3b, v59
	v_exp_f32_e32 v53, v53
	s_nop 0
	v_add_f32_e32 v53, 1.0, v53
	v_rcp_f32_e32 v57, v53
	s_nop 0
	v_pk_mul_f32 v[56:57], v[58:59], v[56:57]
	s_nop 0
	v_pk_mul_f32 v[54:55], v[54:55], v[56:57]
	s_nop 0
	v_cvt_pk_bf16_f32 v53, v54, v55
	v_mul_f32_e32 v54, 0xbfb8aa3b, v48
	v_mul_f32_e32 v55, 0xbfb8aa3b, v49
	v_exp_f32_e32 v54, v54
	v_exp_f32_e32 v55, v55
	v_mov_b32_e32 v150, v52
	v_mov_b32_e32 v151, v53
	s_nop 1
	v_permlane16_swap_b32_e32 v148, v150
	v_permlane16_swap_b32_e32 v149, v151
	global_store_dwordx4 v[62:63], v[148:151], off
	v_add_u32_e32 v52, 0x90, v143
	v_add_f32_e32 v54, 1.0, v54
	v_add_f32_e32 v55, 1.0, v55
	v_rcp_f32_e32 v54, v54
	v_rcp_f32_e32 v55, v55
	v_mad_i64_i32 v[52:53], s[0:1], v52, s2, v[138:139]
	v_pk_mul_f32 v[48:49], v[48:49], v[54:55]
	s_nop 0
	v_pk_mul_f32 v[44:45], v[44:45], v[48:49]
	s_nop 0
	v_cvt_pk_bf16_f32 v44, v44, v45
	v_mul_f32_e32 v45, 0xbfb8aa3b, v50
	v_exp_f32_e32 v45, v45
	s_nop 0
	v_add_f32_e32 v45, 1.0, v45
	v_rcp_f32_e32 v48, v45
	v_mul_f32_e32 v45, 0xbfb8aa3b, v51
	v_exp_f32_e32 v45, v45
	s_nop 0
	v_add_f32_e32 v45, 1.0, v45
	v_rcp_f32_e32 v49, v45
	s_nop 0
	v_pk_mul_f32 v[48:49], v[50:51], v[48:49]
	s_nop 0
	v_pk_mul_f32 v[46:47], v[46:47], v[48:49]
	s_nop 0
	v_cvt_pk_bf16_f32 v45, v46, v47
	v_lshl_add_u64 v[46:47], v[52:53], 0, v[124:125]
	v_mov_b32_e32 v148, v44
	v_mov_b32_e32 v149, v45
	v_mul_f32_e32 v44, 0xbfb8aa3b, v40
	v_mul_f32_e32 v45, 0xbfb8aa3b, v41
	v_exp_f32_e32 v44, v44
	v_exp_f32_e32 v45, v45
	v_add_f32_e32 v44, 1.0, v44
	v_add_f32_e32 v45, 1.0, v45
	v_rcp_f32_e32 v44, v44
	v_rcp_f32_e32 v45, v45
	s_nop 0
	v_pk_mul_f32 v[40:41], v[40:41], v[44:45]
	s_nop 0
	v_pk_mul_f32 v[36:37], v[36:37], v[40:41]
	s_nop 0
	v_cvt_pk_bf16_f32 v36, v36, v37
	v_mul_f32_e32 v37, 0xbfb8aa3b, v42
	v_exp_f32_e32 v37, v37
	s_nop 0
	v_add_f32_e32 v37, 1.0, v37
	v_rcp_f32_e32 v40, v37
	v_mul_f32_e32 v37, 0xbfb8aa3b, v43
	v_exp_f32_e32 v37, v37
	s_nop 0
	v_add_f32_e32 v37, 1.0, v37
	v_rcp_f32_e32 v41, v37
	s_nop 0
	v_pk_mul_f32 v[40:41], v[42:43], v[40:41]
	s_nop 0
	v_pk_mul_f32 v[38:39], v[38:39], v[40:41]
	s_nop 0
	v_cvt_pk_bf16_f32 v37, v38, v39
	v_mul_f32_e32 v38, 0xbfb8aa3b, v32
	v_mul_f32_e32 v39, 0xbfb8aa3b, v33
	v_exp_f32_e32 v38, v38
	v_exp_f32_e32 v39, v39
	v_mov_b32_e32 v150, v36
	v_mov_b32_e32 v151, v37
	s_nop 1
	v_permlane16_swap_b32_e32 v148, v150
	v_permlane16_swap_b32_e32 v149, v151
	global_store_dwordx4 v[46:47], v[148:151], off
	v_add_u32_e32 v36, 0xa0, v143
; __device__ __forceinline__ float siluf_(float x) { return x * sigmoidf_(x); }
;   __device__ __forceinline__ void operator()(const f32x4 (&acc)[2][2][4][2], const Unit& u, int wr, int wc, int fr, int fq) const {
;     const int row0 = u.pm * BM + wr * 64 + fr;
; #pragma unroll
;     for (int ai = 0; ai < 2; ++ai)
; #pragma unroll
;       for (int m = 0; m < 4; ++m) {
;         bfu* rowp = act + (size_t)(row0 + ai * HALF + m * 16) * DFF;
; #pragma unroll
;         for (int bj = 0; bj < 2; ++bj) {
;           const int oc = (u.pn * BM + bj * HALF + wc * 32) / 2 + 4 * fq;
;           const f32x4 g = acc[ai][bj][m][0], up = acc[ai][bj][m][1];
;           uint2 o;
;           o.x = pack2(siluf_(g[0]) * up[0], siluf_(g[1]) * up[1]);
;           o.y = pack2(siluf_(g[2]) * up[2], siluf_(g[3]) * up[3]);
;           *reinterpret_cast<uint2*>(rowp + oc) = o;
;         }
;       }
;   }
	v_add_f32_e32 v38, 1.0, v38
	v_add_f32_e32 v39, 1.0, v39
	v_rcp_f32_e32 v38, v38
	v_rcp_f32_e32 v39, v39
	v_mad_i64_i32 v[36:37], s[0:1], v36, s2, v[138:139]
	v_pk_mul_f32 v[32:33], v[32:33], v[38:39]
	s_nop 0
	v_pk_mul_f32 v[28:29], v[28:29], v[32:33]
	s_nop 0
	v_cvt_pk_bf16_f32 v28, v28, v29
	v_mul_f32_e32 v29, 0xbfb8aa3b, v34
	v_exp_f32_e32 v29, v29
	s_nop 0
	v_add_f32_e32 v29, 1.0, v29
	v_rcp_f32_e32 v32, v29
	v_mul_f32_e32 v29, 0xbfb8aa3b, v35
	v_exp_f32_e32 v29, v29
	s_nop 0
	v_add_f32_e32 v29, 1.0, v29
	v_rcp_f32_e32 v33, v29
	s_nop 0
	v_pk_mul_f32 v[32:33], v[34:35], v[32:33]
	s_nop 0
	v_pk_mul_f32 v[30:31], v[30:31], v[32:33]
	s_nop 0
	v_cvt_pk_bf16_f32 v29, v30, v31
	v_lshl_add_u64 v[30:31], v[36:37], 0, v[124:125]
	v_mov_b32_e32 v148, v28
	v_mov_b32_e32 v149, v29
	v_mul_f32_e32 v28, 0xbfb8aa3b, v24
	v_mul_f32_e32 v29, 0xbfb8aa3b, v25
	v_exp_f32_e32 v28, v28
	v_exp_f32_e32 v29, v29
	v_add_f32_e32 v28, 1.0, v28
	v_add_f32_e32 v29, 1.0, v29
	v_rcp_f32_e32 v28, v28
	v_rcp_f32_e32 v29, v29
	s_nop 0
	v_pk_mul_f32 v[24:25], v[24:25], v[28:29]
	s_nop 0
	v_pk_mul_f32 v[20:21], v[20:21], v[24:25]
	s_nop 0
	v_cvt_pk_bf16_f32 v20, v20, v21
	v_mul_f32_e32 v21, 0xbfb8aa3b, v26
	v_exp_f32_e32 v21, v21
	s_nop 0
	v_add_f32_e32 v21, 1.0, v21
	v_rcp_f32_e32 v24, v21
	v_mul_f32_e32 v21, 0xbfb8aa3b, v27
	v_exp_f32_e32 v21, v21
	s_nop 0
	v_add_f32_e32 v21, 1.0, v21
	v_rcp_f32_e32 v25, v21
	s_nop 0
	v_pk_mul_f32 v[24:25], v[26:27], v[24:25]
	s_nop 0
	v_pk_mul_f32 v[22:23], v[22:23], v[24:25]
	s_nop 0
	v_cvt_pk_bf16_f32 v21, v22, v23
	v_mul_f32_e32 v22, 0xbfb8aa3b, v12
	v_mul_f32_e32 v23, 0xbfb8aa3b, v13
	v_exp_f32_e32 v22, v22
	v_exp_f32_e32 v23, v23
	v_mov_b32_e32 v150, v20
	v_mov_b32_e32 v151, v21
	s_nop 1
	v_permlane16_swap_b32_e32 v148, v150
	v_permlane16_swap_b32_e32 v149, v151
	global_store_dwordx4 v[30:31], v[148:151], off
	v_add_u32_e32 v20, 0xb0, v143
	v_add_f32_e32 v22, 1.0, v22
	v_add_f32_e32 v23, 1.0, v23
	v_rcp_f32_e32 v22, v22
	v_rcp_f32_e32 v23, v23
	v_mad_i64_i32 v[20:21], s[0:1], v20, s2, v[138:139]
	s_mov_b64 s[2:3], s[46:47]
	v_pk_mul_f32 v[12:13], v[12:13], v[22:23]
	s_mov_b32 s46, 0xf800000
	v_pk_mul_f32 v[8:9], v[8:9], v[12:13]
	s_nop 0
	v_cvt_pk_bf16_f32 v8, v8, v9
	v_mul_f32_e32 v9, 0xbfb8aa3b, v14
	v_exp_f32_e32 v9, v9
	s_nop 0
	v_add_f32_e32 v9, 1.0, v9
	v_rcp_f32_e32 v12, v9
	v_mul_f32_e32 v9, 0xbfb8aa3b, v15
	v_exp_f32_e32 v9, v9
	s_nop 0
	v_add_f32_e32 v9, 1.0, v9
	v_rcp_f32_e32 v13, v9
	s_nop 0
	v_pk_mul_f32 v[12:13], v[14:15], v[12:13]
	s_nop 0
	v_pk_mul_f32 v[10:11], v[10:11], v[12:13]
	s_nop 0
	v_cvt_pk_bf16_f32 v9, v10, v11
	v_lshl_add_u64 v[10:11], v[20:21], 0, v[124:125]
	v_mov_b32_e32 v148, v8
	v_mov_b32_e32 v149, v9
	v_mul_f32_e32 v8, 0xbfb8aa3b, v4
	v_mul_f32_e32 v9, 0xbfb8aa3b, v5
	v_exp_f32_e32 v8, v8
	v_exp_f32_e32 v9, v9
	v_add_f32_e32 v8, 1.0, v8
	v_add_f32_e32 v9, 1.0, v9
	v_rcp_f32_e32 v8, v8
	v_rcp_f32_e32 v9, v9
	s_nop 0
	v_pk_mul_f32 v[4:5], v[4:5], v[8:9]
	s_nop 0
	v_pk_mul_f32 v[0:1], v[0:1], v[4:5]
	s_nop 0
	v_cvt_pk_bf16_f32 v0, v0, v1
	v_mul_f32_e32 v1, 0xbfb8aa3b, v6
	v_exp_f32_e32 v1, v1
	s_nop 0
	v_add_f32_e32 v1, 1.0, v1
	v_rcp_f32_e32 v4, v1
	v_mul_f32_e32 v1, 0xbfb8aa3b, v7
	v_exp_f32_e32 v1, v1
	s_nop 0
	v_add_f32_e32 v1, 1.0, v1
	v_rcp_f32_e32 v5, v1
	s_nop 0
	v_pk_mul_f32 v[4:5], v[6:7], v[4:5]
	s_nop 0
	v_pk_mul_f32 v[2:3], v[2:3], v[4:5]
	s_nop 0
	v_cvt_pk_bf16_f32 v1, v2, v3
	v_mov_b32_e32 v150, v0
	v_mov_b32_e32 v151, v1
	s_nop 1
	v_permlane16_swap_b32_e32 v148, v150
	v_permlane16_swap_b32_e32 v149, v151
	global_store_dwordx4 v[10:11], v[148:151], off
	s_cbranch_vccz .LBB0_839
	s_waitcnt vmcnt(0)
	s_cmpk_gt_u32 s74, 0xff
	s_cbranch_scc1 .LBB0_851
	s_barrier
